# GEMM K-loops: counter/pointer increments and exit test moved above the loop-back barrier (back-edge rotation)
# baseline (speedup 1.0000x reference)
; #define PG8_STAGE(bufoff, gbase, voff) do { _Pragma("unroll") for (int _i = 0; _i < 2; ++_i) \
;         __builtin_amdgcn_global_load_lds((const unsigned*)((const char*)(gbase) + (voff)[_i]), (PG8_LAS unsigned*)(lds + (bufoff) + ldsw + _i * 8192), 16, 0, 0); } while (0)
; #define PG8_LDA(dst, b, h) do { _Pragma("unroll") for (int m = 0; m < 4; ++m) _Pragma("unroll") for (int k = 0; k < 2; ++k) dst[m][k] = *(const PG8_LAS bf16x8*)(lds + PG8_SA(b, h) + aoff + m * 2048 + k * 1024); } while (0)
; #define PG8_LDB(dst, b, h) do { _Pragma("unroll") for (int n = 0; n < 2; ++n) _Pragma("unroll") for (int k = 0; k < 2; ++k) dst[n][k] = *(const PG8_LAS bf16x8*)(lds + PG8_SB(b, h) + boff + n * 2048 + k * 1024); } while (0)
; #define PG8_MMA(ai, bj, At, Bt) do { __builtin_amdgcn_s_setprio(1); _Pragma("unroll") for (int m = 0; m < 4; ++m) _Pragma("unroll") for (int n = 0; n < 2; ++n) _Pragma("unroll") for (int k = 0; k < 2; ++k) \
;         acc[ai][bj][m][n] = __builtin_amdgcn_mfma_f32_16x16x32_bf16(Bt[n][k], At[m][k], acc[ai][bj][m][n], 0, 0, 0); __builtin_amdgcn_s_setprio(0); } while (0)
; #define PG8_WAIT_V(n) asm volatile("s_waitcnt vmcnt(" #n ")" ::: "memory")
; #define PG8_WAIT_L(n) asm volatile("s_waitcnt lgkmcnt(" #n ")" ::: "memory")
; #define PG8_BAR __builtin_amdgcn_s_barrier()
; #define PG8_SCHED __builtin_amdgcn_sched_barrier(0)
; template <class Epi, class Sched, bool ALIGN_EPI = false, bool SP2 = false>
; __device__ __forceinline__ void gemm_phase(PG8_LAS unsigned char* lds, const Gemm g, const Sched& S, const Epi& E) {
;     ...
;             if constexpr (SP2) {
;             PG8_LDB(B0, 0, 0); PG8_LDB(B1, 0, 1); PG8_SCHED; PG8_LDA(At, 0, 0); PG8_STAGE(PG8_SA(1, 1), a1 + hstep, voffA);
;             PG8_WAIT_V(8); PG8_WAIT_L(0); PG8_BAR; PG8_MMA(0, 0, At, B0); PG8_MMA(0, 1, At, B1); PG8_BAR; PG8_SCHED;
;             PG8_LDA(At, 0, 1); PG8_STAGE(PG8_SB(0, 0), b2, voffB); PG8_STAGE(PG8_SB(0, 1), b2 + hstep, voffB); PG8_STAGE(PG8_SA(0, 0), a2, voffA);
;             PG8_WAIT_V(8); PG8_WAIT_L(0); PG8_BAR; PG8_MMA(1, 0, At, B0); PG8_MMA(1, 1, At, B1); PG8_BAR; PG8_SCHED;
.LBB0_291:
	ds_read_b128 v[24:27], v204
	ds_read_b128 v[28:31], v204 offset:1024
	ds_read_b128 v[40:43], v204 offset:2048
	ds_read_b128 v[44:47], v204 offset:3072
	ds_read_b128 v[56:59], v205
	ds_read_b128 v[60:63], v205 offset:1024
	ds_read_b128 v[72:75], v205 offset:2048
	ds_read_b128 v[76:79], v205 offset:3072
	s_add_u32 s10, s8, 0xfff80080
	s_addc_u32 s11, s9, -1
	s_cmp_eq_u32 s47, 28
	s_cselect_b32 s45, s3, s11
	s_cselect_b32 s44, s7, s10
	s_cselect_b32 s11, s33, s46
	s_cselect_b32 s10, s37, s39
	v_lshl_add_u64 v[182:183], s[8:9], 0, v[174:175]
	s_add_i32 m0, s50, 0xc000
	ds_read_b128 v[188:191], v206
	ds_read_b128 v[192:195], v206 offset:1024
	ds_read_b128 v[196:199], v206 offset:2048
	ds_read_b128 v[208:211], v206 offset:3072
	ds_read_b128 v[212:215], v206 offset:4096
	ds_read_b128 v[216:219], v206 offset:5120
	ds_read_b128 v[220:223], v206 offset:6144
	ds_read_b128 v[224:227], v206 offset:7168
	global_load_lds_dwordx4 v[182:183], off
	v_lshl_add_u64 v[182:183], s[8:9], 0, v[176:177]
	s_add_i32 m0, s50, 0xe000
	s_nop 0
	global_load_lds_dwordx4 v[182:183], off
	s_waitcnt vmcnt(8)
	s_waitcnt lgkmcnt(0)
	s_barrier
	s_setprio 1
	s_waitcnt lgkmcnt(0)
	v_mfma_f32_16x16x32_bf16 v[156:159], v[24:27], v[188:191], v[156:159]
	v_mfma_f32_16x16x32_bf16 v[152:155], v[40:43], v[188:191], v[152:155]
	v_mfma_f32_16x16x32_bf16 v[140:143], v[24:27], v[196:199], v[140:143]
	v_mfma_f32_16x16x32_bf16 v[136:139], v[40:43], v[196:199], v[136:139]
	v_mfma_f32_16x16x32_bf16 v[124:127], v[24:27], v[212:215], v[124:127]
	v_mfma_f32_16x16x32_bf16 v[120:123], v[40:43], v[212:215], v[120:123]
	v_mfma_f32_16x16x32_bf16 v[108:111], v[24:27], v[220:223], v[108:111]
	v_mfma_f32_16x16x32_bf16 v[104:107], v[40:43], v[220:223], v[104:107]
	v_mfma_f32_16x16x32_bf16 v[156:159], v[28:31], v[192:195], v[156:159]
	v_mfma_f32_16x16x32_bf16 v[152:155], v[44:47], v[192:195], v[152:155]
	v_mfma_f32_16x16x32_bf16 v[140:143], v[28:31], v[208:211], v[140:143]
	v_mfma_f32_16x16x32_bf16 v[136:139], v[44:47], v[208:211], v[136:139]
	v_mfma_f32_16x16x32_bf16 v[124:127], v[28:31], v[216:219], v[124:127]
	v_mfma_f32_16x16x32_bf16 v[120:123], v[44:47], v[216:219], v[120:123]
	v_mfma_f32_16x16x32_bf16 v[108:111], v[28:31], v[224:227], v[108:111]
	v_mfma_f32_16x16x32_bf16 v[104:107], v[44:47], v[224:227], v[104:107]
	s_setprio 0
	s_setprio 1
	v_mfma_f32_16x16x32_bf16 v[148:151], v[56:59], v[188:191], v[148:151]
	v_mfma_f32_16x16x32_bf16 v[144:147], v[72:75], v[188:191], v[144:147]
	v_mfma_f32_16x16x32_bf16 v[132:135], v[56:59], v[196:199], v[132:135]
	v_mfma_f32_16x16x32_bf16 v[128:131], v[72:75], v[196:199], v[128:131]
	v_mfma_f32_16x16x32_bf16 v[116:119], v[56:59], v[212:215], v[116:119]
	v_mfma_f32_16x16x32_bf16 v[112:115], v[72:75], v[212:215], v[112:115]
	v_mfma_f32_16x16x32_bf16 v[100:103], v[56:59], v[220:223], v[100:103]
	v_mfma_f32_16x16x32_bf16 v[96:99], v[72:75], v[220:223], v[96:99]
	v_mfma_f32_16x16x32_bf16 v[148:151], v[60:63], v[192:195], v[148:151]
	v_mfma_f32_16x16x32_bf16 v[144:147], v[76:79], v[192:195], v[144:147]
	v_mfma_f32_16x16x32_bf16 v[132:135], v[60:63], v[208:211], v[132:135]
	v_mfma_f32_16x16x32_bf16 v[128:131], v[76:79], v[208:211], v[128:131]
	v_mfma_f32_16x16x32_bf16 v[116:119], v[60:63], v[216:219], v[116:119]
	v_mfma_f32_16x16x32_bf16 v[112:115], v[76:79], v[216:219], v[112:115]
	v_mfma_f32_16x16x32_bf16 v[100:103], v[60:63], v[224:227], v[100:103]
	v_mfma_f32_16x16x32_bf16 v[96:99], v[76:79], v[224:227], v[96:99]
	s_setprio 0
	s_barrier
	s_add_i32 s48, s60, s35
	v_lshl_add_u64 v[182:183], s[10:11], 0, v[162:163]
	s_mov_b32 m0, s48
	ds_read_b128 v[188:191], v206 offset:16384
	ds_read_b128 v[192:195], v206 offset:17408
	ds_read_b128 v[196:199], v206 offset:18432
	ds_read_b128 v[208:211], v206 offset:19456
	ds_read_b128 v[212:215], v206 offset:20480
	ds_read_b128 v[216:219], v206 offset:21504
	ds_read_b128 v[220:223], v206 offset:22528
	ds_read_b128 v[224:227], v206 offset:23552
	global_load_lds_dwordx4 v[182:183], off
	s_add_i32 m0, s48, 0x2000
	s_add_u32 s48, s10, 0x80000
	v_lshl_add_u64 v[200:201], s[10:11], 0, v[166:167]
	s_addc_u32 s49, s11, 0
	s_add_i32 s64, s61, s35
	global_load_lds_dwordx4 v[200:201], off
	v_lshl_add_u64 v[228:229], s[48:49], 0, v[162:163]
	s_mov_b32 m0, s64
	v_lshl_add_u64 v[232:233], s[44:45], 0, v[160:161]
	global_load_lds_dwordx4 v[228:229], off
	v_lshl_add_u64 v[228:229], s[48:49], 0, v[166:167]
	s_add_i32 m0, s64, 0x2000
	v_lshl_add_u64 v[234:235], s[44:45], 0, v[164:165]
	global_load_lds_dwordx4 v[228:229], off
	s_mov_b32 m0, s50
	s_nop 0
	global_load_lds_dwordx4 v[232:233], off
	s_mov_b32 m0, s51
	s_nop 0
	global_load_lds_dwordx4 v[234:235], off
	s_waitcnt vmcnt(8)
	s_waitcnt lgkmcnt(0)
	s_barrier
; #define PG8_STAGE(bufoff, gbase, voff) do { _Pragma("unroll") for (int _i = 0; _i < 2; ++_i) \
;         __builtin_amdgcn_global_load_lds((const unsigned*)((const char*)(gbase) + (voff)[_i]), (PG8_LAS unsigned*)(lds + (bufoff) + ldsw + _i * 8192), 16, 0, 0); } while (0)
; #define PG8_LDA(dst, b, h) do { _Pragma("unroll") for (int m = 0; m < 4; ++m) _Pragma("unroll") for (int k = 0; k < 2; ++k) dst[m][k] = *(const PG8_LAS bf16x8*)(lds + PG8_SA(b, h) + aoff + m * 2048 + k * 1024); } while (0)
; #define PG8_LDB(dst, b, h) do { _Pragma("unroll") for (int n = 0; n < 2; ++n) _Pragma("unroll") for (int k = 0; k < 2; ++k) dst[n][k] = *(const PG8_LAS bf16x8*)(lds + PG8_SB(b, h) + boff + n * 2048 + k * 1024); } while (0)
; #define PG8_MMA(ai, bj, At, Bt) do { __builtin_amdgcn_s_setprio(1); _Pragma("unroll") for (int m = 0; m < 4; ++m) _Pragma("unroll") for (int n = 0; n < 2; ++n) _Pragma("unroll") for (int k = 0; k < 2; ++k) \
;         acc[ai][bj][m][n] = __builtin_amdgcn_mfma_f32_16x16x32_bf16(Bt[n][k], At[m][k], acc[ai][bj][m][n], 0, 0, 0); __builtin_amdgcn_s_setprio(0); } while (0)
; #define PG8_WAIT_V(n) asm volatile("s_waitcnt vmcnt(" #n ")" ::: "memory")
; #define PG8_WAIT_L(n) asm volatile("s_waitcnt lgkmcnt(" #n ")" ::: "memory")
; #define PG8_BAR __builtin_amdgcn_s_barrier()
; #define PG8_SCHED __builtin_amdgcn_sched_barrier(0)
; template <class Epi, class Sched, bool ALIGN_EPI = false, bool SP2 = false>
; __device__ __forceinline__ void gemm_phase(PG8_LAS unsigned char* lds, const Gemm g, const Sched& S, const Epi& E) {
;     ...
;             PG8_WAIT_V(8); PG8_WAIT_L(0); PG8_BAR; PG8_MMA(1, 0, At, B0); PG8_MMA(1, 1, At, B1); PG8_BAR; PG8_SCHED;
;             PG8_LDB(B0, 1, 0); PG8_LDB(B1, 1, 1); PG8_SCHED; PG8_LDA(At, 1, 0); PG8_STAGE(PG8_SA(0, 1), a2 + hstep, voffA);
;             PG8_WAIT_V(8); PG8_WAIT_L(0); PG8_BAR; PG8_MMA(0, 0, At, B0); PG8_MMA(0, 1, At, B1); PG8_BAR; PG8_SCHED;
	s_setprio 1
	s_waitcnt lgkmcnt(0)
	v_mfma_f32_16x16x32_bf16 v[92:95], v[24:27], v[188:191], v[92:95]
	v_mfma_f32_16x16x32_bf16 v[88:91], v[40:43], v[188:191], v[88:91]
	v_mfma_f32_16x16x32_bf16 v[68:71], v[24:27], v[196:199], v[68:71]
	v_mfma_f32_16x16x32_bf16 v[64:67], v[40:43], v[196:199], v[64:67]
	v_mfma_f32_16x16x32_bf16 v[36:39], v[24:27], v[212:215], v[36:39]
	v_mfma_f32_16x16x32_bf16 v[32:35], v[40:43], v[212:215], v[32:35]
	v_mfma_f32_16x16x32_bf16 v[12:15], v[24:27], v[220:223], v[12:15]
	v_mfma_f32_16x16x32_bf16 v[8:11], v[40:43], v[220:223], v[8:11]
	v_mfma_f32_16x16x32_bf16 v[92:95], v[28:31], v[192:195], v[92:95]
	v_mfma_f32_16x16x32_bf16 v[88:91], v[44:47], v[192:195], v[88:91]
	v_mfma_f32_16x16x32_bf16 v[68:71], v[28:31], v[208:211], v[68:71]
	v_mfma_f32_16x16x32_bf16 v[64:67], v[44:47], v[208:211], v[64:67]
	v_mfma_f32_16x16x32_bf16 v[36:39], v[28:31], v[216:219], v[36:39]
	v_mfma_f32_16x16x32_bf16 v[32:35], v[44:47], v[216:219], v[32:35]
	v_mfma_f32_16x16x32_bf16 v[12:15], v[28:31], v[224:227], v[12:15]
	v_mfma_f32_16x16x32_bf16 v[8:11], v[44:47], v[224:227], v[8:11]
	s_setprio 0
	s_setprio 1
	v_mfma_f32_16x16x32_bf16 v[20:23], v[56:59], v[212:215], v[20:23]
	v_mfma_f32_16x16x32_bf16 v[16:19], v[72:75], v[212:215], v[16:19]
	v_mfma_f32_16x16x32_bf16 v[4:7], v[56:59], v[220:223], v[4:7]
	v_mfma_f32_16x16x32_bf16 v[0:3], v[72:75], v[220:223], v[0:3]
	v_mfma_f32_16x16x32_bf16 v[24:27], v[56:59], v[188:191], v[84:87]
	v_mfma_f32_16x16x32_bf16 v[28:31], v[72:75], v[188:191], v[80:83]
	v_mfma_f32_16x16x32_bf16 v[40:43], v[56:59], v[196:199], v[52:55]
	v_mfma_f32_16x16x32_bf16 v[44:47], v[72:75], v[196:199], v[48:51]
	v_mfma_f32_16x16x32_bf16 v[20:23], v[60:63], v[216:219], v[20:23]
	v_mfma_f32_16x16x32_bf16 v[16:19], v[76:79], v[216:219], v[16:19]
	v_mfma_f32_16x16x32_bf16 v[4:7], v[60:63], v[224:227], v[4:7]
	v_mfma_f32_16x16x32_bf16 v[0:3], v[76:79], v[224:227], v[0:3]
	v_mfma_f32_16x16x32_bf16 v[24:27], v[60:63], v[192:195], v[24:27]
	v_mfma_f32_16x16x32_bf16 v[28:31], v[76:79], v[192:195], v[28:31]
	v_mfma_f32_16x16x32_bf16 v[40:43], v[60:63], v[208:211], v[40:43]
	v_mfma_f32_16x16x32_bf16 v[44:47], v[76:79], v[208:211], v[44:47]
	s_setprio 0
	s_barrier
	s_add_i32 s48, 0, 0x18000
	s_add_i32 s49, 0, 0x1c000
	v_add_u32_e32 v60, s48, v187
	v_add_u32_e32 v80, s49, v187
	ds_read_b128 v[48:51], v60
	ds_read_b128 v[52:55], v60 offset:1024
	ds_read_b128 v[56:59], v60 offset:2048
	ds_read_b128 v[60:63], v60 offset:3072
	ds_read_b128 v[72:75], v80
	ds_read_b128 v[76:79], v80 offset:1024
	ds_read_b128 v[188:191], v80 offset:2048
	ds_read_b128 v[192:195], v80 offset:3072
	s_add_u32 s44, s44, 0x80000
	s_addc_u32 s45, s45, 0
	s_mov_b32 m0, s52
	v_lshl_add_u64 v[228:229], s[44:45], 0, v[160:161]
	ds_read_b128 v[80:83], v206 offset:32768
	ds_read_b128 v[84:87], v206 offset:33792
	ds_read_b128 v[196:199], v206 offset:34816
	ds_read_b128 v[208:211], v206 offset:35840
	ds_read_b128 v[212:215], v206 offset:36864
	ds_read_b128 v[216:219], v206 offset:37888
	ds_read_b128 v[220:223], v206 offset:38912
	ds_read_b128 v[224:227], v206 offset:39936
	global_load_lds_dwordx4 v[228:229], off
	v_lshl_add_u64 v[228:229], s[44:45], 0, v[164:165]
	s_mov_b32 m0, s53
	s_nop 0
	global_load_lds_dwordx4 v[228:229], off
	s_waitcnt vmcnt(8)
	s_waitcnt lgkmcnt(0)
	s_barrier
	s_setprio 1
	s_waitcnt lgkmcnt(0)
	v_mfma_f32_16x16x32_bf16 v[156:159], v[48:51], v[80:83], v[156:159]
	v_mfma_f32_16x16x32_bf16 v[152:155], v[56:59], v[80:83], v[152:155]
	v_mfma_f32_16x16x32_bf16 v[140:143], v[48:51], v[196:199], v[140:143]
	v_mfma_f32_16x16x32_bf16 v[136:139], v[56:59], v[196:199], v[136:139]
	v_mfma_f32_16x16x32_bf16 v[124:127], v[48:51], v[212:215], v[124:127]
	v_mfma_f32_16x16x32_bf16 v[120:123], v[56:59], v[212:215], v[120:123]
	v_mfma_f32_16x16x32_bf16 v[108:111], v[48:51], v[220:223], v[108:111]
	v_mfma_f32_16x16x32_bf16 v[104:107], v[56:59], v[220:223], v[104:107]
	v_mfma_f32_16x16x32_bf16 v[156:159], v[52:55], v[84:87], v[156:159]
	v_mfma_f32_16x16x32_bf16 v[152:155], v[60:63], v[84:87], v[152:155]
	v_mfma_f32_16x16x32_bf16 v[140:143], v[52:55], v[208:211], v[140:143]
	v_mfma_f32_16x16x32_bf16 v[136:139], v[60:63], v[208:211], v[136:139]
	v_mfma_f32_16x16x32_bf16 v[124:127], v[52:55], v[216:219], v[124:127]
	v_mfma_f32_16x16x32_bf16 v[120:123], v[60:63], v[216:219], v[120:123]
	v_mfma_f32_16x16x32_bf16 v[108:111], v[52:55], v[224:227], v[108:111]
	v_mfma_f32_16x16x32_bf16 v[104:107], v[60:63], v[224:227], v[104:107]
	s_setprio 0
	s_setprio 1
	v_mfma_f32_16x16x32_bf16 v[148:151], v[72:75], v[80:83], v[148:151]
	v_mfma_f32_16x16x32_bf16 v[80:83], v[188:191], v[80:83], v[144:147]
	v_mfma_f32_16x16x32_bf16 v[144:147], v[192:195], v[84:87], v[80:83]
	v_mfma_f32_16x16x32_bf16 v[80:83], v[72:75], v[196:199], v[132:135]
	v_mfma_f32_16x16x32_bf16 v[132:135], v[76:79], v[208:211], v[80:83]
	v_mfma_f32_16x16x32_bf16 v[80:83], v[188:191], v[196:199], v[128:131]
	v_mfma_f32_16x16x32_bf16 v[128:131], v[192:195], v[208:211], v[80:83]
	v_mfma_f32_16x16x32_bf16 v[80:83], v[72:75], v[212:215], v[116:119]
	v_mfma_f32_16x16x32_bf16 v[116:119], v[76:79], v[216:219], v[80:83]
	v_mfma_f32_16x16x32_bf16 v[80:83], v[188:191], v[212:215], v[112:115]
	v_mfma_f32_16x16x32_bf16 v[112:115], v[192:195], v[216:219], v[80:83]
	v_mfma_f32_16x16x32_bf16 v[80:83], v[72:75], v[220:223], v[100:103]
	v_mfma_f32_16x16x32_bf16 v[100:103], v[76:79], v[224:227], v[80:83]
	v_mfma_f32_16x16x32_bf16 v[80:83], v[188:191], v[220:223], v[96:99]
	v_mfma_f32_16x16x32_bf16 v[148:151], v[76:79], v[84:87], v[148:151]
	v_mfma_f32_16x16x32_bf16 v[96:99], v[192:195], v[224:227], v[80:83]
	s_setprio 0
	s_barrier
; #define PG8_STAGE(bufoff, gbase, voff) do { _Pragma("unroll") for (int _i = 0; _i < 2; ++_i) \
;         __builtin_amdgcn_global_load_lds((const unsigned*)((const char*)(gbase) + (voff)[_i]), (PG8_LAS unsigned*)(lds + (bufoff) + ldsw + _i * 8192), 16, 0, 0); } while (0)
; #define PG8_LDA(dst, b, h) do { _Pragma("unroll") for (int m = 0; m < 4; ++m) _Pragma("unroll") for (int k = 0; k < 2; ++k) dst[m][k] = *(const PG8_LAS bf16x8*)(lds + PG8_SA(b, h) + aoff + m * 2048 + k * 1024); } while (0)
; #define PG8_MMA(ai, bj, At, Bt) do { __builtin_amdgcn_s_setprio(1); _Pragma("unroll") for (int m = 0; m < 4; ++m) _Pragma("unroll") for (int n = 0; n < 2; ++n) _Pragma("unroll") for (int k = 0; k < 2; ++k) \
;         acc[ai][bj][m][n] = __builtin_amdgcn_mfma_f32_16x16x32_bf16(Bt[n][k], At[m][k], acc[ai][bj][m][n], 0, 0, 0); __builtin_amdgcn_s_setprio(0); } while (0)
; #define PG8_WAIT_V(n) asm volatile("s_waitcnt vmcnt(" #n ")" ::: "memory")
; #define PG8_WAIT_L(n) asm volatile("s_waitcnt lgkmcnt(" #n ")" ::: "memory")
; #define PG8_BAR __builtin_amdgcn_s_barrier()
; #define PG8_SCHED __builtin_amdgcn_sched_barrier(0)
; template <class Epi, class Sched, bool ALIGN_EPI = false, bool SP2 = false>
; __device__ __forceinline__ void gemm_phase(PG8_LAS unsigned char* lds, const Gemm g, const Sched& S, const Epi& E) {
;     ...
;         for (int t = 0; t < nt; t += 2) {
;     ...
;             PG8_LDA(At, 1, 1); PG8_STAGE(PG8_SB(1, 0), b3, voffB); PG8_STAGE(PG8_SB(1, 1), b3 + hstep, voffB); PG8_STAGE(PG8_SA(1, 0), a3, voffA);
;             PG8_WAIT_V(8); PG8_WAIT_L(0); PG8_BAR; PG8_MMA(1, 0, At, B0); PG8_MMA(1, 1, At, B1); PG8_BAR; PG8_SCHED;
	s_add_i32 s44, s48, s35
	v_lshl_add_u64 v[84:85], v[182:183], 0, s[24:25]
	s_mov_b32 m0, s44
	s_nop 0
	ds_read_b128 v[80:83], v206 offset:49152
	ds_read_b128 v[196:199], v206 offset:50176
	ds_read_b128 v[208:211], v206 offset:51200
	ds_read_b128 v[212:215], v206 offset:52224
	ds_read_b128 v[216:219], v206 offset:53248
	ds_read_b128 v[220:223], v206 offset:54272
	ds_read_b128 v[224:227], v206 offset:55296
	ds_read_b128 v[228:231], v206 offset:56320
	global_load_lds_dwordx4 v[84:85], off
	s_add_i32 m0, s44, 0x2000
	s_add_u32 s10, s10, 0x80080
	v_lshl_add_u64 v[84:85], v[200:201], 0, s[24:25]
	s_addc_u32 s11, s11, 0
	s_add_i32 s44, s49, s35
	global_load_lds_dwordx4 v[84:85], off
	v_lshl_add_u64 v[84:85], s[10:11], 0, v[162:163]
	s_mov_b32 m0, s44
	s_nop 0
	global_load_lds_dwordx4 v[84:85], off
	v_lshl_add_u64 v[84:85], s[10:11], 0, v[166:167]
	s_add_i32 m0, s44, 0x2000
	s_nop 0
	global_load_lds_dwordx4 v[84:85], off
	v_lshl_add_u64 v[84:85], v[232:233], 0, s[24:25]
	s_mov_b32 m0, s55
	s_nop 0
	global_load_lds_dwordx4 v[84:85], off
	v_lshl_add_u64 v[84:85], v[234:235], 0, s[24:25]
	s_mov_b32 m0, s56
	s_nop 0
	global_load_lds_dwordx4 v[84:85], off
	s_waitcnt vmcnt(8)
	s_waitcnt lgkmcnt(0)
	s_barrier
	s_setprio 1
	s_waitcnt lgkmcnt(0)
	v_mfma_f32_16x16x32_bf16 v[84:87], v[48:51], v[80:83], v[92:95]
	v_mfma_f32_16x16x32_bf16 v[92:95], v[52:55], v[196:199], v[84:87]
	v_mfma_f32_16x16x32_bf16 v[84:87], v[56:59], v[80:83], v[88:91]
	v_mfma_f32_16x16x32_bf16 v[68:71], v[48:51], v[208:211], v[68:71]
	v_mfma_f32_16x16x32_bf16 v[64:67], v[56:59], v[208:211], v[64:67]
	v_mfma_f32_16x16x32_bf16 v[36:39], v[48:51], v[216:219], v[36:39]
	v_mfma_f32_16x16x32_bf16 v[32:35], v[56:59], v[216:219], v[32:35]
	v_mfma_f32_16x16x32_bf16 v[12:15], v[48:51], v[224:227], v[12:15]
	v_mfma_f32_16x16x32_bf16 v[8:11], v[56:59], v[224:227], v[8:11]
	v_mfma_f32_16x16x32_bf16 v[88:91], v[60:63], v[196:199], v[84:87]
	v_mfma_f32_16x16x32_bf16 v[68:71], v[52:55], v[212:215], v[68:71]
	v_mfma_f32_16x16x32_bf16 v[64:67], v[60:63], v[212:215], v[64:67]
	v_mfma_f32_16x16x32_bf16 v[36:39], v[52:55], v[220:223], v[36:39]
	v_mfma_f32_16x16x32_bf16 v[32:35], v[60:63], v[220:223], v[32:35]
	v_mfma_f32_16x16x32_bf16 v[12:15], v[52:55], v[228:231], v[12:15]
	v_mfma_f32_16x16x32_bf16 v[8:11], v[60:63], v[228:231], v[8:11]
	s_setprio 0
	s_setprio 1
	v_mfma_f32_16x16x32_bf16 v[24:27], v[72:75], v[80:83], v[24:27]
	v_mfma_f32_16x16x32_bf16 v[84:87], v[76:79], v[196:199], v[24:27]
	v_mfma_f32_16x16x32_bf16 v[24:27], v[188:191], v[80:83], v[28:31]
	v_mfma_f32_16x16x32_bf16 v[80:83], v[192:195], v[196:199], v[24:27]
	v_mfma_f32_16x16x32_bf16 v[24:27], v[72:75], v[208:211], v[40:43]
	v_mfma_f32_16x16x32_bf16 v[52:55], v[76:79], v[212:215], v[24:27]
	v_mfma_f32_16x16x32_bf16 v[24:27], v[188:191], v[208:211], v[44:47]
	v_mfma_f32_16x16x32_bf16 v[20:23], v[72:75], v[216:219], v[20:23]
	v_mfma_f32_16x16x32_bf16 v[16:19], v[188:191], v[216:219], v[16:19]
	v_mfma_f32_16x16x32_bf16 v[4:7], v[72:75], v[224:227], v[4:7]
	v_mfma_f32_16x16x32_bf16 v[0:3], v[188:191], v[224:227], v[0:3]
	v_mfma_f32_16x16x32_bf16 v[48:51], v[192:195], v[212:215], v[24:27]
	v_mfma_f32_16x16x32_bf16 v[20:23], v[76:79], v[220:223], v[20:23]
	v_mfma_f32_16x16x32_bf16 v[16:19], v[192:195], v[220:223], v[16:19]
	v_mfma_f32_16x16x32_bf16 v[4:7], v[76:79], v[228:231], v[4:7]
	v_mfma_f32_16x16x32_bf16 v[0:3], v[192:195], v[228:231], v[0:3]
	s_setprio 0
	s_add_i32 s47, s47, 2
	s_add_u32 s8, s8, 0x100
	s_addc_u32 s9, s9, 0
	s_add_u32 s39, s39, 0x100
	s_addc_u32 s46, s46, 0
	s_cmp_gt_u32 s47, 29
	s_barrier
	s_cbranch_scc0 .LBB0_291
	s_and_b64 vcc, exec, s[26:27]
	s_cbranch_vccz .LBB0_294
	s_barrier

; #define PG8_STAGE(bufoff, gbase, voff) do { _Pragma("unroll") for (int _i = 0; _i < 2; ++_i) \
;         __builtin_amdgcn_global_load_lds((const unsigned*)((const char*)(gbase) + (voff)[_i]), (PG8_LAS unsigned*)(lds + (bufoff) + ldsw + _i * 8192), 16, 0, 0); } while (0)
; #define PG8_LDA(dst, b, h) do { _Pragma("unroll") for (int m = 0; m < 4; ++m) _Pragma("unroll") for (int k = 0; k < 2; ++k) dst[m][k] = *(const PG8_LAS bf16x8*)(lds + PG8_SA(b, h) + aoff + m * 2048 + k * 1024); } while (0)
; #define PG8_LDB(dst, b, h) do { _Pragma("unroll") for (int n = 0; n < 2; ++n) _Pragma("unroll") for (int k = 0; k < 2; ++k) dst[n][k] = *(const PG8_LAS bf16x8*)(lds + PG8_SB(b, h) + boff + n * 2048 + k * 1024); } while (0)
; #define PG8_MMA(ai, bj, At, Bt) do { __builtin_amdgcn_s_setprio(1); _Pragma("unroll") for (int m = 0; m < 4; ++m) _Pragma("unroll") for (int n = 0; n < 2; ++n) _Pragma("unroll") for (int k = 0; k < 2; ++k) \
;         acc[ai][bj][m][n] = __builtin_amdgcn_mfma_f32_16x16x32_bf16(Bt[n][k], At[m][k], acc[ai][bj][m][n], 0, 0, 0); __builtin_amdgcn_s_setprio(0); } while (0)
; #define PG8_WAIT_V(n) asm volatile("s_waitcnt vmcnt(" #n ")" ::: "memory")
; #define PG8_WAIT_L(n) asm volatile("s_waitcnt lgkmcnt(" #n ")" ::: "memory")
; #define PG8_BAR __builtin_amdgcn_s_barrier()
; #define PG8_SCHED __builtin_amdgcn_sched_barrier(0)
; template <class Epi, class Sched, bool ALIGN_EPI = false, bool SP2 = false>
; __device__ __forceinline__ void gemm_phase(PG8_LAS unsigned char* lds, const Gemm g, const Sched& S, const Epi& E) {
;     ...
;             if constexpr (SP2) {
;             PG8_LDB(B0, 0, 0); PG8_LDB(B1, 0, 1); PG8_SCHED; PG8_LDA(At, 0, 0); PG8_STAGE(PG8_SA(1, 1), a1 + hstep, voffA);
;             PG8_WAIT_V(8); PG8_WAIT_L(0); PG8_BAR; PG8_MMA(0, 0, At, B0); PG8_MMA(0, 1, At, B1); PG8_BAR; PG8_SCHED;
;             PG8_LDA(At, 0, 1); PG8_STAGE(PG8_SB(0, 0), b2, voffB); PG8_STAGE(PG8_SB(0, 1), b2 + hstep, voffB); PG8_STAGE(PG8_SA(0, 0), a2, voffA);
;             PG8_WAIT_V(8); PG8_WAIT_L(0); PG8_BAR; PG8_MMA(1, 0, At, B0); PG8_MMA(1, 1, At, B1); PG8_BAR; PG8_SCHED;
.LBB0_883:
	ds_read_b128 v[128:131], v179
	ds_read_b128 v[132:135], v179 offset:1024
	ds_read_b128 v[136:139], v179 offset:2048
	ds_read_b128 v[140:143], v179 offset:3072
	ds_read_b128 v[144:147], v180
	ds_read_b128 v[148:151], v180 offset:1024
	ds_read_b128 v[168:171], v180 offset:2048
	ds_read_b128 v[172:175], v180 offset:3072
	s_add_u32 s26, s24, 0xfffc0080
	s_addc_u32 s27, s25, -1
	s_cmp_eq_u32 s48, 12
	s_cselect_b32 s29, s19, s27
	s_cselect_b32 s28, s44, s26
	s_cselect_b32 s27, s17, s47
	s_cselect_b32 s26, s45, s46
	v_lshl_add_u64 v[182:183], s[24:25], 0, v[160:161]
	s_add_i32 m0, s34, 0xc000
	ds_read_b128 v[188:191], v181
	ds_read_b128 v[192:195], v181 offset:1024
	ds_read_b128 v[196:199], v181 offset:2048
	ds_read_b128 v[200:203], v181 offset:3072
	ds_read_b128 v[204:207], v181 offset:4096
	ds_read_b128 v[208:211], v181 offset:5120
	ds_read_b128 v[212:215], v181 offset:6144
	ds_read_b128 v[216:219], v181 offset:7168
	global_load_lds_dwordx4 v[182:183], off
	v_lshl_add_u64 v[182:183], s[24:25], 0, v[162:163]
	s_add_i32 m0, s34, 0xe000
	s_nop 0
	global_load_lds_dwordx4 v[182:183], off
	s_waitcnt vmcnt(8)
	s_waitcnt lgkmcnt(0)
	s_barrier
	s_setprio 1
	s_waitcnt lgkmcnt(0)
	v_mfma_f32_16x16x32_bf16 v[124:127], v[128:131], v[188:191], v[124:127]
	v_mfma_f32_16x16x32_bf16 v[120:123], v[136:139], v[188:191], v[120:123]
	v_mfma_f32_16x16x32_bf16 v[108:111], v[128:131], v[196:199], v[108:111]
	v_mfma_f32_16x16x32_bf16 v[104:107], v[136:139], v[196:199], v[104:107]
	v_mfma_f32_16x16x32_bf16 v[92:95], v[128:131], v[204:207], v[92:95]
	v_mfma_f32_16x16x32_bf16 v[88:91], v[136:139], v[204:207], v[88:91]
	v_mfma_f32_16x16x32_bf16 v[76:79], v[128:131], v[212:215], v[76:79]
	v_mfma_f32_16x16x32_bf16 v[72:75], v[136:139], v[212:215], v[72:75]
	v_mfma_f32_16x16x32_bf16 v[124:127], v[132:135], v[192:195], v[124:127]
	v_mfma_f32_16x16x32_bf16 v[120:123], v[140:143], v[192:195], v[120:123]
	v_mfma_f32_16x16x32_bf16 v[108:111], v[132:135], v[200:203], v[108:111]
	v_mfma_f32_16x16x32_bf16 v[104:107], v[140:143], v[200:203], v[104:107]
	v_mfma_f32_16x16x32_bf16 v[92:95], v[132:135], v[208:211], v[92:95]
	v_mfma_f32_16x16x32_bf16 v[88:91], v[140:143], v[208:211], v[88:91]
	v_mfma_f32_16x16x32_bf16 v[76:79], v[132:135], v[216:219], v[76:79]
	v_mfma_f32_16x16x32_bf16 v[72:75], v[140:143], v[216:219], v[72:75]
	s_setprio 0
	s_setprio 1
	v_mfma_f32_16x16x32_bf16 v[116:119], v[144:147], v[188:191], v[116:119]
	v_mfma_f32_16x16x32_bf16 v[112:115], v[168:171], v[188:191], v[112:115]
	v_mfma_f32_16x16x32_bf16 v[100:103], v[144:147], v[196:199], v[100:103]
	v_mfma_f32_16x16x32_bf16 v[96:99], v[168:171], v[196:199], v[96:99]
	v_mfma_f32_16x16x32_bf16 v[84:87], v[144:147], v[204:207], v[84:87]
	v_mfma_f32_16x16x32_bf16 v[80:83], v[168:171], v[204:207], v[80:83]
	v_mfma_f32_16x16x32_bf16 v[68:71], v[144:147], v[212:215], v[68:71]
	v_mfma_f32_16x16x32_bf16 v[64:67], v[168:171], v[212:215], v[64:67]
	v_mfma_f32_16x16x32_bf16 v[116:119], v[148:151], v[192:195], v[116:119]
	v_mfma_f32_16x16x32_bf16 v[112:115], v[172:175], v[192:195], v[112:115]
	v_mfma_f32_16x16x32_bf16 v[100:103], v[148:151], v[200:203], v[100:103]
	v_mfma_f32_16x16x32_bf16 v[96:99], v[172:175], v[200:203], v[96:99]
	v_mfma_f32_16x16x32_bf16 v[84:87], v[148:151], v[208:211], v[84:87]
	v_mfma_f32_16x16x32_bf16 v[80:83], v[172:175], v[208:211], v[80:83]
	v_mfma_f32_16x16x32_bf16 v[68:71], v[148:151], v[216:219], v[68:71]
	v_mfma_f32_16x16x32_bf16 v[64:67], v[172:175], v[216:219], v[64:67]
	s_setprio 0
	s_barrier
	s_add_i32 s49, s42, s31
	v_lshl_add_u64 v[182:183], s[26:27], 0, v[154:155]
	s_mov_b32 m0, s49
	ds_read_b128 v[188:191], v181 offset:16384
	ds_read_b128 v[192:195], v181 offset:17408
	ds_read_b128 v[196:199], v181 offset:18432
	ds_read_b128 v[200:203], v181 offset:19456
	ds_read_b128 v[204:207], v181 offset:20480
	ds_read_b128 v[208:211], v181 offset:21504
	ds_read_b128 v[212:215], v181 offset:22528
	ds_read_b128 v[216:219], v181 offset:23552
	global_load_lds_dwordx4 v[182:183], off
	s_add_i32 m0, s49, 0x2000
	s_add_u32 s50, s26, 0x40000
	v_lshl_add_u64 v[220:221], s[26:27], 0, v[158:159]
	s_addc_u32 s51, s27, 0
	s_add_i32 s49, s43, s31
	global_load_lds_dwordx4 v[220:221], off
	v_lshl_add_u64 v[222:223], s[50:51], 0, v[154:155]
	s_mov_b32 m0, s49
	v_lshl_add_u64 v[224:225], s[28:29], 0, v[156:157]
	global_load_lds_dwordx4 v[222:223], off
	v_lshl_add_u64 v[222:223], s[50:51], 0, v[158:159]
	s_add_i32 m0, s49, 0x2000
	s_nop 0
	global_load_lds_dwordx4 v[222:223], off
	v_lshl_add_u64 v[222:223], s[28:29], 0, v[152:153]
	s_mov_b32 m0, s34
	s_nop 0
	global_load_lds_dwordx4 v[222:223], off
	s_mov_b32 m0, s33
	s_nop 0
	global_load_lds_dwordx4 v[224:225], off
	s_waitcnt vmcnt(8)
	s_waitcnt lgkmcnt(0)
	s_barrier
; #define PG8_STAGE(bufoff, gbase, voff) do { _Pragma("unroll") for (int _i = 0; _i < 2; ++_i) \
;         __builtin_amdgcn_global_load_lds((const unsigned*)((const char*)(gbase) + (voff)[_i]), (PG8_LAS unsigned*)(lds + (bufoff) + ldsw + _i * 8192), 16, 0, 0); } while (0)
; #define PG8_LDA(dst, b, h) do { _Pragma("unroll") for (int m = 0; m < 4; ++m) _Pragma("unroll") for (int k = 0; k < 2; ++k) dst[m][k] = *(const PG8_LAS bf16x8*)(lds + PG8_SA(b, h) + aoff + m * 2048 + k * 1024); } while (0)
; #define PG8_LDB(dst, b, h) do { _Pragma("unroll") for (int n = 0; n < 2; ++n) _Pragma("unroll") for (int k = 0; k < 2; ++k) dst[n][k] = *(const PG8_LAS bf16x8*)(lds + PG8_SB(b, h) + boff + n * 2048 + k * 1024); } while (0)
; #define PG8_MMA(ai, bj, At, Bt) do { __builtin_amdgcn_s_setprio(1); _Pragma("unroll") for (int m = 0; m < 4; ++m) _Pragma("unroll") for (int n = 0; n < 2; ++n) _Pragma("unroll") for (int k = 0; k < 2; ++k) \
;         acc[ai][bj][m][n] = __builtin_amdgcn_mfma_f32_16x16x32_bf16(Bt[n][k], At[m][k], acc[ai][bj][m][n], 0, 0, 0); __builtin_amdgcn_s_setprio(0); } while (0)
; #define PG8_WAIT_V(n) asm volatile("s_waitcnt vmcnt(" #n ")" ::: "memory")
; #define PG8_WAIT_L(n) asm volatile("s_waitcnt lgkmcnt(" #n ")" ::: "memory")
; #define PG8_BAR __builtin_amdgcn_s_barrier()
; #define PG8_SCHED __builtin_amdgcn_sched_barrier(0)
; template <class Epi, class Sched, bool ALIGN_EPI = false, bool SP2 = false>
; __device__ __forceinline__ void gemm_phase(PG8_LAS unsigned char* lds, const Gemm g, const Sched& S, const Epi& E) {
;     ...
;             PG8_WAIT_V(8); PG8_WAIT_L(0); PG8_BAR; PG8_MMA(1, 0, At, B0); PG8_MMA(1, 1, At, B1); PG8_BAR; PG8_SCHED;
;             PG8_LDB(B0, 1, 0); PG8_LDB(B1, 1, 1); PG8_SCHED; PG8_LDA(At, 1, 0); PG8_STAGE(PG8_SA(0, 1), a2 + hstep, voffA);
;             PG8_WAIT_V(8); PG8_WAIT_L(0); PG8_BAR; PG8_MMA(0, 0, At, B0); PG8_MMA(0, 1, At, B1); PG8_BAR; PG8_SCHED;
	s_setprio 1
	s_waitcnt lgkmcnt(0)
	v_mfma_f32_16x16x32_bf16 v[60:63], v[128:131], v[188:191], v[60:63]
	v_mfma_f32_16x16x32_bf16 v[56:59], v[136:139], v[188:191], v[56:59]
	v_mfma_f32_16x16x32_bf16 v[44:47], v[128:131], v[196:199], v[44:47]
	v_mfma_f32_16x16x32_bf16 v[40:43], v[136:139], v[196:199], v[40:43]
	v_mfma_f32_16x16x32_bf16 v[28:31], v[128:131], v[204:207], v[28:31]
	v_mfma_f32_16x16x32_bf16 v[24:27], v[136:139], v[204:207], v[24:27]
	v_mfma_f32_16x16x32_bf16 v[12:15], v[128:131], v[212:215], v[12:15]
	v_mfma_f32_16x16x32_bf16 v[8:11], v[136:139], v[212:215], v[8:11]
	v_mfma_f32_16x16x32_bf16 v[60:63], v[132:135], v[192:195], v[60:63]
	v_mfma_f32_16x16x32_bf16 v[56:59], v[140:143], v[192:195], v[56:59]
	v_mfma_f32_16x16x32_bf16 v[44:47], v[132:135], v[200:203], v[44:47]
	v_mfma_f32_16x16x32_bf16 v[40:43], v[140:143], v[200:203], v[40:43]
	v_mfma_f32_16x16x32_bf16 v[28:31], v[132:135], v[208:211], v[28:31]
	v_mfma_f32_16x16x32_bf16 v[24:27], v[140:143], v[208:211], v[24:27]
	v_mfma_f32_16x16x32_bf16 v[12:15], v[132:135], v[216:219], v[12:15]
	v_mfma_f32_16x16x32_bf16 v[8:11], v[140:143], v[216:219], v[8:11]
	s_setprio 0
	s_setprio 1
	v_mfma_f32_16x16x32_bf16 v[52:55], v[144:147], v[188:191], v[52:55]
	v_mfma_f32_16x16x32_bf16 v[48:51], v[168:171], v[188:191], v[48:51]
	v_mfma_f32_16x16x32_bf16 v[36:39], v[144:147], v[196:199], v[36:39]
	v_mfma_f32_16x16x32_bf16 v[32:35], v[168:171], v[196:199], v[32:35]
	v_mfma_f32_16x16x32_bf16 v[20:23], v[144:147], v[204:207], v[20:23]
	v_mfma_f32_16x16x32_bf16 v[16:19], v[168:171], v[204:207], v[16:19]
	v_mfma_f32_16x16x32_bf16 v[4:7], v[144:147], v[212:215], v[4:7]
	v_mfma_f32_16x16x32_bf16 v[0:3], v[168:171], v[212:215], v[0:3]
	v_mfma_f32_16x16x32_bf16 v[52:55], v[148:151], v[192:195], v[52:55]
	v_mfma_f32_16x16x32_bf16 v[48:51], v[172:175], v[192:195], v[48:51]
	v_mfma_f32_16x16x32_bf16 v[36:39], v[148:151], v[200:203], v[36:39]
	v_mfma_f32_16x16x32_bf16 v[32:35], v[172:175], v[200:203], v[32:35]
	v_mfma_f32_16x16x32_bf16 v[20:23], v[148:151], v[208:211], v[20:23]
	v_mfma_f32_16x16x32_bf16 v[16:19], v[172:175], v[208:211], v[16:19]
	v_mfma_f32_16x16x32_bf16 v[4:7], v[148:151], v[216:219], v[4:7]
	v_mfma_f32_16x16x32_bf16 v[0:3], v[172:175], v[216:219], v[0:3]
	s_setprio 0
	s_barrier
	s_add_i32 s49, 0, 0x18000
	s_add_i32 s50, 0, 0x1c000
	v_add_u32_e32 v140, s49, v177
	v_add_u32_e32 v172, s50, v177
	ds_read_b128 v[128:131], v140
	ds_read_b128 v[132:135], v140 offset:1024
	ds_read_b128 v[136:139], v140 offset:2048
	ds_read_b128 v[140:143], v140 offset:3072
	ds_read_b128 v[144:147], v172
	ds_read_b128 v[148:151], v172 offset:1024
	ds_read_b128 v[168:171], v172 offset:2048
	ds_read_b128 v[172:175], v172 offset:3072
	s_add_u32 s28, s28, 0x40000
	s_addc_u32 s29, s29, 0
	s_mov_b32 m0, s35
	v_lshl_add_u64 v[226:227], s[28:29], 0, v[152:153]
	ds_read_b128 v[188:191], v181 offset:32768
	ds_read_b128 v[192:195], v181 offset:33792
	ds_read_b128 v[196:199], v181 offset:34816
	ds_read_b128 v[200:203], v181 offset:35840
	ds_read_b128 v[204:207], v181 offset:36864
	ds_read_b128 v[208:211], v181 offset:37888
	ds_read_b128 v[212:215], v181 offset:38912
	ds_read_b128 v[216:219], v181 offset:39936
	global_load_lds_dwordx4 v[226:227], off
	v_lshl_add_u64 v[226:227], s[28:29], 0, v[156:157]
	s_mov_b32 m0, s36
	s_nop 0
	global_load_lds_dwordx4 v[226:227], off
	s_waitcnt vmcnt(8)
	s_waitcnt lgkmcnt(0)
	s_barrier
	s_setprio 1
	s_waitcnt lgkmcnt(0)
	v_mfma_f32_16x16x32_bf16 v[124:127], v[128:131], v[188:191], v[124:127]
	v_mfma_f32_16x16x32_bf16 v[120:123], v[136:139], v[188:191], v[120:123]
	v_mfma_f32_16x16x32_bf16 v[108:111], v[128:131], v[196:199], v[108:111]
	v_mfma_f32_16x16x32_bf16 v[104:107], v[136:139], v[196:199], v[104:107]
	v_mfma_f32_16x16x32_bf16 v[92:95], v[128:131], v[204:207], v[92:95]
	v_mfma_f32_16x16x32_bf16 v[88:91], v[136:139], v[204:207], v[88:91]
	v_mfma_f32_16x16x32_bf16 v[76:79], v[128:131], v[212:215], v[76:79]
	v_mfma_f32_16x16x32_bf16 v[72:75], v[136:139], v[212:215], v[72:75]
	v_mfma_f32_16x16x32_bf16 v[124:127], v[132:135], v[192:195], v[124:127]
	v_mfma_f32_16x16x32_bf16 v[120:123], v[140:143], v[192:195], v[120:123]
	v_mfma_f32_16x16x32_bf16 v[108:111], v[132:135], v[200:203], v[108:111]
	v_mfma_f32_16x16x32_bf16 v[104:107], v[140:143], v[200:203], v[104:107]
	v_mfma_f32_16x16x32_bf16 v[92:95], v[132:135], v[208:211], v[92:95]
	v_mfma_f32_16x16x32_bf16 v[88:91], v[140:143], v[208:211], v[88:91]
	v_mfma_f32_16x16x32_bf16 v[76:79], v[132:135], v[216:219], v[76:79]
	v_mfma_f32_16x16x32_bf16 v[72:75], v[140:143], v[216:219], v[72:75]
	s_setprio 0
	s_setprio 1
	v_mfma_f32_16x16x32_bf16 v[116:119], v[144:147], v[188:191], v[116:119]
	v_mfma_f32_16x16x32_bf16 v[112:115], v[168:171], v[188:191], v[112:115]
	v_mfma_f32_16x16x32_bf16 v[100:103], v[144:147], v[196:199], v[100:103]
	v_mfma_f32_16x16x32_bf16 v[96:99], v[168:171], v[196:199], v[96:99]
	v_mfma_f32_16x16x32_bf16 v[84:87], v[144:147], v[204:207], v[84:87]
	v_mfma_f32_16x16x32_bf16 v[80:83], v[168:171], v[204:207], v[80:83]
	v_mfma_f32_16x16x32_bf16 v[68:71], v[144:147], v[212:215], v[68:71]
	v_mfma_f32_16x16x32_bf16 v[64:67], v[168:171], v[212:215], v[64:67]
	v_mfma_f32_16x16x32_bf16 v[116:119], v[148:151], v[192:195], v[116:119]
	v_mfma_f32_16x16x32_bf16 v[112:115], v[172:175], v[192:195], v[112:115]
	v_mfma_f32_16x16x32_bf16 v[100:103], v[148:151], v[200:203], v[100:103]
	v_mfma_f32_16x16x32_bf16 v[96:99], v[172:175], v[200:203], v[96:99]
	v_mfma_f32_16x16x32_bf16 v[84:87], v[148:151], v[208:211], v[84:87]
	v_mfma_f32_16x16x32_bf16 v[80:83], v[172:175], v[208:211], v[80:83]
	v_mfma_f32_16x16x32_bf16 v[68:71], v[148:151], v[216:219], v[68:71]
	v_mfma_f32_16x16x32_bf16 v[64:67], v[172:175], v[216:219], v[64:67]
	s_setprio 0
	s_barrier
; #define PG8_STAGE(bufoff, gbase, voff) do { _Pragma("unroll") for (int _i = 0; _i < 2; ++_i) \
;         __builtin_amdgcn_global_load_lds((const unsigned*)((const char*)(gbase) + (voff)[_i]), (PG8_LAS unsigned*)(lds + (bufoff) + ldsw + _i * 8192), 16, 0, 0); } while (0)
; #define PG8_LDA(dst, b, h) do { _Pragma("unroll") for (int m = 0; m < 4; ++m) _Pragma("unroll") for (int k = 0; k < 2; ++k) dst[m][k] = *(const PG8_LAS bf16x8*)(lds + PG8_SA(b, h) + aoff + m * 2048 + k * 1024); } while (0)
; #define PG8_MMA(ai, bj, At, Bt) do { __builtin_amdgcn_s_setprio(1); _Pragma("unroll") for (int m = 0; m < 4; ++m) _Pragma("unroll") for (int n = 0; n < 2; ++n) _Pragma("unroll") for (int k = 0; k < 2; ++k) \
;         acc[ai][bj][m][n] = __builtin_amdgcn_mfma_f32_16x16x32_bf16(Bt[n][k], At[m][k], acc[ai][bj][m][n], 0, 0, 0); __builtin_amdgcn_s_setprio(0); } while (0)
; #define PG8_WAIT_V(n) asm volatile("s_waitcnt vmcnt(" #n ")" ::: "memory")
; #define PG8_WAIT_L(n) asm volatile("s_waitcnt lgkmcnt(" #n ")" ::: "memory")
; #define PG8_BAR __builtin_amdgcn_s_barrier()
; #define PG8_SCHED __builtin_amdgcn_sched_barrier(0)
; template <class Epi, class Sched, bool ALIGN_EPI = false, bool SP2 = false>
; __device__ __forceinline__ void gemm_phase(PG8_LAS unsigned char* lds, const Gemm g, const Sched& S, const Epi& E) {
;     ...
;             PG8_LDA(At, 1, 1); PG8_STAGE(PG8_SB(1, 0), b3, voffB); PG8_STAGE(PG8_SB(1, 1), b3 + hstep, voffB); PG8_STAGE(PG8_SA(1, 0), a3, voffA);
;             PG8_WAIT_V(8); PG8_WAIT_L(0); PG8_BAR; PG8_MMA(1, 0, At, B0); PG8_MMA(1, 1, At, B1); PG8_BAR; PG8_SCHED;
;     ...
;         if constexpr (ALIGN_EPI) { if (wr == 0) PG8_BAR; }
	s_add_i32 s28, s49, s31
	v_lshl_add_u64 v[182:183], v[182:183], 0, s[8:9]
	s_mov_b32 m0, s28
	ds_read_b128 v[188:191], v181 offset:49152
	ds_read_b128 v[192:195], v181 offset:50176
	ds_read_b128 v[196:199], v181 offset:51200
	ds_read_b128 v[200:203], v181 offset:52224
	ds_read_b128 v[204:207], v181 offset:53248
	ds_read_b128 v[208:211], v181 offset:54272
	ds_read_b128 v[212:215], v181 offset:55296
	ds_read_b128 v[216:219], v181 offset:56320
	global_load_lds_dwordx4 v[182:183], off
	s_add_i32 m0, s28, 0x2000
	s_add_u32 s26, s26, 0x40080
	v_lshl_add_u64 v[182:183], v[220:221], 0, s[8:9]
	s_addc_u32 s27, s27, 0
	s_add_i32 s28, s50, s31
	global_load_lds_dwordx4 v[182:183], off
	v_lshl_add_u64 v[182:183], s[26:27], 0, v[154:155]
	s_mov_b32 m0, s28
	s_nop 0
	global_load_lds_dwordx4 v[182:183], off
	v_lshl_add_u64 v[182:183], s[26:27], 0, v[158:159]
	s_add_i32 m0, s28, 0x2000
	s_nop 0
	global_load_lds_dwordx4 v[182:183], off
	v_lshl_add_u64 v[182:183], v[222:223], 0, s[8:9]
	s_mov_b32 m0, s38
	s_nop 0
	global_load_lds_dwordx4 v[182:183], off
	v_lshl_add_u64 v[182:183], v[224:225], 0, s[8:9]
	s_mov_b32 m0, s39
	s_nop 0
	global_load_lds_dwordx4 v[182:183], off
	s_waitcnt vmcnt(8)
	s_waitcnt lgkmcnt(0)
	s_barrier
	s_setprio 1
	s_waitcnt lgkmcnt(0)
	v_mfma_f32_16x16x32_bf16 v[60:63], v[128:131], v[188:191], v[60:63]
	v_mfma_f32_16x16x32_bf16 v[56:59], v[136:139], v[188:191], v[56:59]
	v_mfma_f32_16x16x32_bf16 v[44:47], v[128:131], v[196:199], v[44:47]
	v_mfma_f32_16x16x32_bf16 v[40:43], v[136:139], v[196:199], v[40:43]
	v_mfma_f32_16x16x32_bf16 v[28:31], v[128:131], v[204:207], v[28:31]
	v_mfma_f32_16x16x32_bf16 v[24:27], v[136:139], v[204:207], v[24:27]
	v_mfma_f32_16x16x32_bf16 v[12:15], v[128:131], v[212:215], v[12:15]
	v_mfma_f32_16x16x32_bf16 v[8:11], v[136:139], v[212:215], v[8:11]
	v_mfma_f32_16x16x32_bf16 v[60:63], v[132:135], v[192:195], v[60:63]
	v_mfma_f32_16x16x32_bf16 v[56:59], v[140:143], v[192:195], v[56:59]
	v_mfma_f32_16x16x32_bf16 v[44:47], v[132:135], v[200:203], v[44:47]
	v_mfma_f32_16x16x32_bf16 v[40:43], v[140:143], v[200:203], v[40:43]
	v_mfma_f32_16x16x32_bf16 v[28:31], v[132:135], v[208:211], v[28:31]
	v_mfma_f32_16x16x32_bf16 v[24:27], v[140:143], v[208:211], v[24:27]
	v_mfma_f32_16x16x32_bf16 v[12:15], v[132:135], v[216:219], v[12:15]
	v_mfma_f32_16x16x32_bf16 v[8:11], v[140:143], v[216:219], v[8:11]
	s_setprio 0
	s_setprio 1
	v_mfma_f32_16x16x32_bf16 v[52:55], v[144:147], v[188:191], v[52:55]
	v_mfma_f32_16x16x32_bf16 v[48:51], v[168:171], v[188:191], v[48:51]
	v_mfma_f32_16x16x32_bf16 v[36:39], v[144:147], v[196:199], v[36:39]
	v_mfma_f32_16x16x32_bf16 v[32:35], v[168:171], v[196:199], v[32:35]
	v_mfma_f32_16x16x32_bf16 v[20:23], v[144:147], v[204:207], v[20:23]
	v_mfma_f32_16x16x32_bf16 v[16:19], v[168:171], v[204:207], v[16:19]
	v_mfma_f32_16x16x32_bf16 v[4:7], v[144:147], v[212:215], v[4:7]
	v_mfma_f32_16x16x32_bf16 v[0:3], v[168:171], v[212:215], v[0:3]
	v_mfma_f32_16x16x32_bf16 v[52:55], v[148:151], v[192:195], v[52:55]
	v_mfma_f32_16x16x32_bf16 v[48:51], v[172:175], v[192:195], v[48:51]
	v_mfma_f32_16x16x32_bf16 v[36:39], v[148:151], v[200:203], v[36:39]
	v_mfma_f32_16x16x32_bf16 v[32:35], v[172:175], v[200:203], v[32:35]
	v_mfma_f32_16x16x32_bf16 v[20:23], v[148:151], v[208:211], v[20:23]
	v_mfma_f32_16x16x32_bf16 v[16:19], v[172:175], v[208:211], v[16:19]
	v_mfma_f32_16x16x32_bf16 v[4:7], v[148:151], v[216:219], v[4:7]
	v_mfma_f32_16x16x32_bf16 v[0:3], v[172:175], v[216:219], v[0:3]
	s_setprio 0
	s_add_i32 s48, s48, 2
	s_add_u32 s24, s24, 0x100
	s_addc_u32 s25, s25, 0
	s_add_u32 s46, s46, 0x100
	s_addc_u32 s47, s47, 0
	s_cmp_gt_u32 s48, 13
	s_barrier
	s_cbranch_scc0 .LBB0_883
	s_and_b64 vcc, exec, s[14:15]
	s_cbranch_vccz .LBB0_886
	s_barrier

; #define PG8_STAGE(bufoff, gbase, voff) do { _Pragma("unroll") for (int _i = 0; _i < 2; ++_i) \
;         __builtin_amdgcn_global_load_lds((const unsigned*)((const char*)(gbase) + (voff)[_i]), (PG8_LAS unsigned*)(lds + (bufoff) + ldsw + _i * 8192), 16, 0, 0); } while (0)
; #define PG8_LDA(dst, b, h) do { _Pragma("unroll") for (int m = 0; m < 4; ++m) _Pragma("unroll") for (int k = 0; k < 2; ++k) dst[m][k] = *(const PG8_LAS bf16x8*)(lds + PG8_SA(b, h) + aoff + m * 2048 + k * 1024); } while (0)
; #define PG8_LDB(dst, b, h) do { _Pragma("unroll") for (int n = 0; n < 2; ++n) _Pragma("unroll") for (int k = 0; k < 2; ++k) dst[n][k] = *(const PG8_LAS bf16x8*)(lds + PG8_SB(b, h) + boff + n * 2048 + k * 1024); } while (0)
; #define PG8_MMA(ai, bj, At, Bt) do { __builtin_amdgcn_s_setprio(1); _Pragma("unroll") for (int m = 0; m < 4; ++m) _Pragma("unroll") for (int n = 0; n < 2; ++n) _Pragma("unroll") for (int k = 0; k < 2; ++k) \
;         acc[ai][bj][m][n] = __builtin_amdgcn_mfma_f32_16x16x32_bf16(Bt[n][k], At[m][k], acc[ai][bj][m][n], 0, 0, 0); __builtin_amdgcn_s_setprio(0); } while (0)
; #define PG8_WAIT_V(n) asm volatile("s_waitcnt vmcnt(" #n ")" ::: "memory")
; #define PG8_WAIT_L(n) asm volatile("s_waitcnt lgkmcnt(" #n ")" ::: "memory")
; #define PG8_BAR __builtin_amdgcn_s_barrier()
; #define PG8_SCHED __builtin_amdgcn_sched_barrier(0)
; template <class Epi, class Sched, bool ALIGN_EPI = false, bool SP2 = false>
; __device__ __forceinline__ void gemm_phase(PG8_LAS unsigned char* lds, const Gemm g, const Sched& S, const Epi& E) {
;     ...
;             const bool last = (t == nt - 2);
;             const char* a1 = cA + (size_t)(t + 1) * kstep;
;             const char* a2 = last ? nA : cA + (size_t)(t + 2) * kstep; const char* b2 = last ? nB : cB + (size_t)(t + 2) * kstep;
;             const char* a3 = a2 + kstep; const char* b3 = b2 + kstep;
;             if (last && has_next) S.a_ready(nxt);
;             if constexpr (SP2) {
;             PG8_LDB(B0, 0, 0); PG8_LDB(B1, 0, 1); PG8_SCHED; PG8_LDA(At, 0, 0); PG8_STAGE(PG8_SA(1, 1), a1 + hstep, voffA);
;             PG8_WAIT_V(8); PG8_WAIT_L(0); PG8_BAR; PG8_MMA(0, 0, At, B0); PG8_MMA(0, 1, At, B1); PG8_BAR; PG8_SCHED;
;             PG8_LDA(At, 0, 1); PG8_STAGE(PG8_SB(0, 0), b2, voffB); PG8_STAGE(PG8_SB(0, 1), b2 + hstep, voffB); PG8_STAGE(PG8_SA(0, 0), a2, voffA);
.LBB0_964:
	ds_read_b128 v[128:131], v161
	ds_read_b128 v[132:135], v161 offset:1024
	ds_read_b128 v[152:155], v161 offset:2048
	ds_read_b128 v[166:169], v161 offset:3072
	ds_read_b128 v[170:173], v162
	ds_read_b128 v[174:177], v162 offset:1024
	ds_read_b128 v[178:181], v162 offset:2048
	ds_read_b128 v[188:191], v162 offset:3072
	s_add_u32 s28, s26, 0xfff80080
	s_addc_u32 s29, s27, -1
	s_cmp_eq_u32 s48, 28
	s_cselect_b32 s31, s3, s29
	s_cselect_b32 s30, s19, s28
	s_cselect_b32 s29, s17, s47
	s_cselect_b32 s28, s45, s46
	v_lshl_add_u64 v[156:157], s[26:27], 0, v[144:145]
	s_add_i32 m0, s25, 0xc000
	ds_read_b128 v[192:195], v163
	ds_read_b128 v[196:199], v163 offset:1024
	ds_read_b128 v[200:203], v163 offset:2048
	ds_read_b128 v[204:207], v163 offset:3072
	ds_read_b128 v[208:211], v163 offset:4096
	ds_read_b128 v[212:215], v163 offset:5120
	ds_read_b128 v[216:219], v163 offset:6144
	ds_read_b128 v[220:223], v163 offset:7168
	global_load_lds_dwordx4 v[156:157], off
	v_lshl_add_u64 v[156:157], s[26:27], 0, v[146:147]
	s_add_i32 m0, s25, 0xe000
	s_nop 0
	global_load_lds_dwordx4 v[156:157], off
	s_waitcnt vmcnt(8)
	s_waitcnt lgkmcnt(0)
	s_barrier
	s_setprio 1
	s_waitcnt lgkmcnt(0)
	v_mfma_f32_16x16x32_bf16 v[124:127], v[128:131], v[192:195], v[124:127]
	v_mfma_f32_16x16x32_bf16 v[120:123], v[152:155], v[192:195], v[120:123]
	v_mfma_f32_16x16x32_bf16 v[108:111], v[128:131], v[200:203], v[108:111]
	v_mfma_f32_16x16x32_bf16 v[104:107], v[152:155], v[200:203], v[104:107]
	v_mfma_f32_16x16x32_bf16 v[92:95], v[128:131], v[208:211], v[92:95]
	v_mfma_f32_16x16x32_bf16 v[88:91], v[152:155], v[208:211], v[88:91]
	v_mfma_f32_16x16x32_bf16 v[76:79], v[128:131], v[216:219], v[76:79]
	v_mfma_f32_16x16x32_bf16 v[72:75], v[152:155], v[216:219], v[72:75]
	v_mfma_f32_16x16x32_bf16 v[124:127], v[132:135], v[196:199], v[124:127]
	v_mfma_f32_16x16x32_bf16 v[120:123], v[166:169], v[196:199], v[120:123]
	v_mfma_f32_16x16x32_bf16 v[108:111], v[132:135], v[204:207], v[108:111]
	v_mfma_f32_16x16x32_bf16 v[104:107], v[166:169], v[204:207], v[104:107]
	v_mfma_f32_16x16x32_bf16 v[92:95], v[132:135], v[212:215], v[92:95]
	v_mfma_f32_16x16x32_bf16 v[88:91], v[166:169], v[212:215], v[88:91]
	v_mfma_f32_16x16x32_bf16 v[76:79], v[132:135], v[220:223], v[76:79]
	v_mfma_f32_16x16x32_bf16 v[72:75], v[166:169], v[220:223], v[72:75]
	s_setprio 0
	s_setprio 1
	v_mfma_f32_16x16x32_bf16 v[116:119], v[170:173], v[192:195], v[116:119]
	v_mfma_f32_16x16x32_bf16 v[112:115], v[178:181], v[192:195], v[112:115]
	v_mfma_f32_16x16x32_bf16 v[100:103], v[170:173], v[200:203], v[100:103]
	v_mfma_f32_16x16x32_bf16 v[96:99], v[178:181], v[200:203], v[96:99]
	v_mfma_f32_16x16x32_bf16 v[84:87], v[170:173], v[208:211], v[84:87]
	v_mfma_f32_16x16x32_bf16 v[80:83], v[178:181], v[208:211], v[80:83]
	v_mfma_f32_16x16x32_bf16 v[68:71], v[170:173], v[216:219], v[68:71]
	v_mfma_f32_16x16x32_bf16 v[64:67], v[178:181], v[216:219], v[64:67]
	v_mfma_f32_16x16x32_bf16 v[116:119], v[174:177], v[196:199], v[116:119]
	v_mfma_f32_16x16x32_bf16 v[112:115], v[188:191], v[196:199], v[112:115]
	v_mfma_f32_16x16x32_bf16 v[100:103], v[174:177], v[204:207], v[100:103]
	v_mfma_f32_16x16x32_bf16 v[96:99], v[188:191], v[204:207], v[96:99]
	v_mfma_f32_16x16x32_bf16 v[84:87], v[174:177], v[212:215], v[84:87]
	v_mfma_f32_16x16x32_bf16 v[80:83], v[188:191], v[212:215], v[80:83]
	v_mfma_f32_16x16x32_bf16 v[68:71], v[174:177], v[220:223], v[68:71]
	v_mfma_f32_16x16x32_bf16 v[64:67], v[188:191], v[220:223], v[64:67]
	s_setprio 0
	s_barrier
	s_add_i32 s49, s43, s33
	v_lshl_add_u64 v[156:157], s[28:29], 0, v[138:139]
	s_mov_b32 m0, s49
	ds_read_b128 v[192:195], v163 offset:16384
	ds_read_b128 v[196:199], v163 offset:17408
	ds_read_b128 v[200:203], v163 offset:18432
	ds_read_b128 v[204:207], v163 offset:19456
	ds_read_b128 v[208:211], v163 offset:20480
	ds_read_b128 v[212:215], v163 offset:21504
	ds_read_b128 v[216:219], v163 offset:22528
	ds_read_b128 v[220:223], v163 offset:23552
	global_load_lds_dwordx4 v[156:157], off
	s_add_i32 m0, s49, 0x2000
	s_add_u32 s50, s28, 0x80000
	v_lshl_add_u64 v[182:183], s[28:29], 0, v[142:143]
	s_addc_u32 s51, s29, 0
	s_add_i32 s49, s44, s33
	global_load_lds_dwordx4 v[182:183], off
	v_lshl_add_u64 v[224:225], s[50:51], 0, v[138:139]
	s_mov_b32 m0, s49
	v_lshl_add_u64 v[226:227], s[30:31], 0, v[140:141]
	global_load_lds_dwordx4 v[224:225], off
	v_lshl_add_u64 v[224:225], s[50:51], 0, v[142:143]
	s_add_i32 m0, s49, 0x2000
	s_nop 0
	global_load_lds_dwordx4 v[224:225], off
	v_lshl_add_u64 v[224:225], s[30:31], 0, v[136:137]
	s_mov_b32 m0, s25
	s_nop 0
	global_load_lds_dwordx4 v[224:225], off
	s_mov_b32 m0, s34
	s_nop 0
	global_load_lds_dwordx4 v[226:227], off
	s_waitcnt vmcnt(8)
	s_waitcnt lgkmcnt(0)
	s_barrier
; #define PG8_STAGE(bufoff, gbase, voff) do { _Pragma("unroll") for (int _i = 0; _i < 2; ++_i) \
;         __builtin_amdgcn_global_load_lds((const unsigned*)((const char*)(gbase) + (voff)[_i]), (PG8_LAS unsigned*)(lds + (bufoff) + ldsw + _i * 8192), 16, 0, 0); } while (0)
; #define PG8_LDA(dst, b, h) do { _Pragma("unroll") for (int m = 0; m < 4; ++m) _Pragma("unroll") for (int k = 0; k < 2; ++k) dst[m][k] = *(const PG8_LAS bf16x8*)(lds + PG8_SA(b, h) + aoff + m * 2048 + k * 1024); } while (0)
; #define PG8_LDB(dst, b, h) do { _Pragma("unroll") for (int n = 0; n < 2; ++n) _Pragma("unroll") for (int k = 0; k < 2; ++k) dst[n][k] = *(const PG8_LAS bf16x8*)(lds + PG8_SB(b, h) + boff + n * 2048 + k * 1024); } while (0)
; #define PG8_MMA(ai, bj, At, Bt) do { __builtin_amdgcn_s_setprio(1); _Pragma("unroll") for (int m = 0; m < 4; ++m) _Pragma("unroll") for (int n = 0; n < 2; ++n) _Pragma("unroll") for (int k = 0; k < 2; ++k) \
;         acc[ai][bj][m][n] = __builtin_amdgcn_mfma_f32_16x16x32_bf16(Bt[n][k], At[m][k], acc[ai][bj][m][n], 0, 0, 0); __builtin_amdgcn_s_setprio(0); } while (0)
; #define PG8_WAIT_V(n) asm volatile("s_waitcnt vmcnt(" #n ")" ::: "memory")
; #define PG8_WAIT_L(n) asm volatile("s_waitcnt lgkmcnt(" #n ")" ::: "memory")
; #define PG8_BAR __builtin_amdgcn_s_barrier()
; #define PG8_SCHED __builtin_amdgcn_sched_barrier(0)
; template <class Epi, class Sched, bool ALIGN_EPI = false, bool SP2 = false>
; __device__ __forceinline__ void gemm_phase(PG8_LAS unsigned char* lds, const Gemm g, const Sched& S, const Epi& E) {
;     ...
;             PG8_WAIT_V(8); PG8_WAIT_L(0); PG8_BAR; PG8_MMA(1, 0, At, B0); PG8_MMA(1, 1, At, B1); PG8_BAR; PG8_SCHED;
;             PG8_LDB(B0, 1, 0); PG8_LDB(B1, 1, 1); PG8_SCHED; PG8_LDA(At, 1, 0); PG8_STAGE(PG8_SA(0, 1), a2 + hstep, voffA);
;             PG8_WAIT_V(8); PG8_WAIT_L(0); PG8_BAR; PG8_MMA(0, 0, At, B0); PG8_MMA(0, 1, At, B1); PG8_BAR; PG8_SCHED;
	s_setprio 1
	s_waitcnt lgkmcnt(0)
	v_mfma_f32_16x16x32_bf16 v[60:63], v[128:131], v[192:195], v[60:63]
	v_mfma_f32_16x16x32_bf16 v[56:59], v[152:155], v[192:195], v[56:59]
	v_mfma_f32_16x16x32_bf16 v[44:47], v[128:131], v[200:203], v[44:47]
	v_mfma_f32_16x16x32_bf16 v[40:43], v[152:155], v[200:203], v[40:43]
	v_mfma_f32_16x16x32_bf16 v[28:31], v[128:131], v[208:211], v[28:31]
	v_mfma_f32_16x16x32_bf16 v[24:27], v[152:155], v[208:211], v[24:27]
	v_mfma_f32_16x16x32_bf16 v[12:15], v[128:131], v[216:219], v[12:15]
	v_mfma_f32_16x16x32_bf16 v[8:11], v[152:155], v[216:219], v[8:11]
	v_mfma_f32_16x16x32_bf16 v[60:63], v[132:135], v[196:199], v[60:63]
	v_mfma_f32_16x16x32_bf16 v[56:59], v[166:169], v[196:199], v[56:59]
	v_mfma_f32_16x16x32_bf16 v[44:47], v[132:135], v[204:207], v[44:47]
	v_mfma_f32_16x16x32_bf16 v[40:43], v[166:169], v[204:207], v[40:43]
	v_mfma_f32_16x16x32_bf16 v[28:31], v[132:135], v[212:215], v[28:31]
	v_mfma_f32_16x16x32_bf16 v[24:27], v[166:169], v[212:215], v[24:27]
	v_mfma_f32_16x16x32_bf16 v[12:15], v[132:135], v[220:223], v[12:15]
	v_mfma_f32_16x16x32_bf16 v[8:11], v[166:169], v[220:223], v[8:11]
	s_setprio 0
	s_setprio 1
	v_mfma_f32_16x16x32_bf16 v[52:55], v[170:173], v[192:195], v[52:55]
	v_mfma_f32_16x16x32_bf16 v[48:51], v[178:181], v[192:195], v[48:51]
	v_mfma_f32_16x16x32_bf16 v[36:39], v[170:173], v[200:203], v[36:39]
	v_mfma_f32_16x16x32_bf16 v[32:35], v[178:181], v[200:203], v[32:35]
	v_mfma_f32_16x16x32_bf16 v[20:23], v[170:173], v[208:211], v[20:23]
	v_mfma_f32_16x16x32_bf16 v[16:19], v[178:181], v[208:211], v[16:19]
	v_mfma_f32_16x16x32_bf16 v[4:7], v[170:173], v[216:219], v[4:7]
	v_mfma_f32_16x16x32_bf16 v[0:3], v[178:181], v[216:219], v[0:3]
	v_mfma_f32_16x16x32_bf16 v[52:55], v[174:177], v[196:199], v[52:55]
	v_mfma_f32_16x16x32_bf16 v[48:51], v[188:191], v[196:199], v[48:51]
	v_mfma_f32_16x16x32_bf16 v[36:39], v[174:177], v[204:207], v[36:39]
	v_mfma_f32_16x16x32_bf16 v[32:35], v[188:191], v[204:207], v[32:35]
	v_mfma_f32_16x16x32_bf16 v[20:23], v[174:177], v[212:215], v[20:23]
	v_mfma_f32_16x16x32_bf16 v[16:19], v[188:191], v[212:215], v[16:19]
	v_mfma_f32_16x16x32_bf16 v[4:7], v[174:177], v[220:223], v[4:7]
	v_mfma_f32_16x16x32_bf16 v[0:3], v[188:191], v[220:223], v[0:3]
	s_setprio 0
	s_barrier
	s_add_i32 s49, 0, 0x18000
	v_add_u32_e32 v165, s49, v159
	s_add_i32 s50, 0, 0x1c000
	ds_read_b128 v[128:131], v165
	ds_read_b128 v[132:135], v165 offset:1024
	ds_read_b128 v[152:155], v165 offset:2048
	ds_read_b128 v[166:169], v165 offset:3072
	v_add_u32_e32 v165, s50, v159
	ds_read_b128 v[170:173], v165
	ds_read_b128 v[174:177], v165 offset:1024
	ds_read_b128 v[178:181], v165 offset:2048
	ds_read_b128 v[188:191], v165 offset:3072
	s_add_u32 s30, s30, 0x80000
	s_addc_u32 s31, s31, 0
	s_mov_b32 m0, s35
	v_lshl_add_u64 v[228:229], s[30:31], 0, v[136:137]
	ds_read_b128 v[192:195], v163 offset:32768
	ds_read_b128 v[196:199], v163 offset:33792
	ds_read_b128 v[200:203], v163 offset:34816
	ds_read_b128 v[204:207], v163 offset:35840
	ds_read_b128 v[208:211], v163 offset:36864
	ds_read_b128 v[212:215], v163 offset:37888
	ds_read_b128 v[216:219], v163 offset:38912
	ds_read_b128 v[220:223], v163 offset:39936
	global_load_lds_dwordx4 v[228:229], off
	v_lshl_add_u64 v[228:229], s[30:31], 0, v[140:141]
	s_mov_b32 m0, s36
	s_nop 0
	global_load_lds_dwordx4 v[228:229], off
	s_waitcnt vmcnt(8)
	s_waitcnt lgkmcnt(0)
	s_barrier
	s_setprio 1
	s_waitcnt lgkmcnt(0)
	v_mfma_f32_16x16x32_bf16 v[124:127], v[128:131], v[192:195], v[124:127]
	v_mfma_f32_16x16x32_bf16 v[120:123], v[152:155], v[192:195], v[120:123]
	v_mfma_f32_16x16x32_bf16 v[108:111], v[128:131], v[200:203], v[108:111]
	v_mfma_f32_16x16x32_bf16 v[104:107], v[152:155], v[200:203], v[104:107]
	v_mfma_f32_16x16x32_bf16 v[92:95], v[128:131], v[208:211], v[92:95]
	v_mfma_f32_16x16x32_bf16 v[88:91], v[152:155], v[208:211], v[88:91]
	v_mfma_f32_16x16x32_bf16 v[76:79], v[128:131], v[216:219], v[76:79]
	v_mfma_f32_16x16x32_bf16 v[72:75], v[152:155], v[216:219], v[72:75]
	v_mfma_f32_16x16x32_bf16 v[124:127], v[132:135], v[196:199], v[124:127]
	v_mfma_f32_16x16x32_bf16 v[120:123], v[166:169], v[196:199], v[120:123]
	v_mfma_f32_16x16x32_bf16 v[108:111], v[132:135], v[204:207], v[108:111]
	v_mfma_f32_16x16x32_bf16 v[104:107], v[166:169], v[204:207], v[104:107]
	v_mfma_f32_16x16x32_bf16 v[92:95], v[132:135], v[212:215], v[92:95]
	v_mfma_f32_16x16x32_bf16 v[88:91], v[166:169], v[212:215], v[88:91]
	v_mfma_f32_16x16x32_bf16 v[76:79], v[132:135], v[220:223], v[76:79]
	v_mfma_f32_16x16x32_bf16 v[72:75], v[166:169], v[220:223], v[72:75]
	s_setprio 0
	s_setprio 1
	v_mfma_f32_16x16x32_bf16 v[116:119], v[170:173], v[192:195], v[116:119]
	v_mfma_f32_16x16x32_bf16 v[112:115], v[178:181], v[192:195], v[112:115]
	v_mfma_f32_16x16x32_bf16 v[100:103], v[170:173], v[200:203], v[100:103]
	v_mfma_f32_16x16x32_bf16 v[96:99], v[178:181], v[200:203], v[96:99]
	v_mfma_f32_16x16x32_bf16 v[84:87], v[170:173], v[208:211], v[84:87]
	v_mfma_f32_16x16x32_bf16 v[80:83], v[178:181], v[208:211], v[80:83]
	v_mfma_f32_16x16x32_bf16 v[68:71], v[170:173], v[216:219], v[68:71]
	v_mfma_f32_16x16x32_bf16 v[64:67], v[178:181], v[216:219], v[64:67]
	v_mfma_f32_16x16x32_bf16 v[116:119], v[174:177], v[196:199], v[116:119]
	v_mfma_f32_16x16x32_bf16 v[112:115], v[188:191], v[196:199], v[112:115]
	v_mfma_f32_16x16x32_bf16 v[100:103], v[174:177], v[204:207], v[100:103]
	v_mfma_f32_16x16x32_bf16 v[96:99], v[188:191], v[204:207], v[96:99]
	v_mfma_f32_16x16x32_bf16 v[84:87], v[174:177], v[212:215], v[84:87]
	v_mfma_f32_16x16x32_bf16 v[80:83], v[188:191], v[212:215], v[80:83]
	v_mfma_f32_16x16x32_bf16 v[68:71], v[174:177], v[220:223], v[68:71]
	v_mfma_f32_16x16x32_bf16 v[64:67], v[188:191], v[220:223], v[64:67]
	s_setprio 0
	s_barrier
; #define PG8_STAGE(bufoff, gbase, voff) do { _Pragma("unroll") for (int _i = 0; _i < 2; ++_i) \
;         __builtin_amdgcn_global_load_lds((const unsigned*)((const char*)(gbase) + (voff)[_i]), (PG8_LAS unsigned*)(lds + (bufoff) + ldsw + _i * 8192), 16, 0, 0); } while (0)
; #define PG8_LDA(dst, b, h) do { _Pragma("unroll") for (int m = 0; m < 4; ++m) _Pragma("unroll") for (int k = 0; k < 2; ++k) dst[m][k] = *(const PG8_LAS bf16x8*)(lds + PG8_SA(b, h) + aoff + m * 2048 + k * 1024); } while (0)
; #define PG8_MMA(ai, bj, At, Bt) do { __builtin_amdgcn_s_setprio(1); _Pragma("unroll") for (int m = 0; m < 4; ++m) _Pragma("unroll") for (int n = 0; n < 2; ++n) _Pragma("unroll") for (int k = 0; k < 2; ++k) \
;         acc[ai][bj][m][n] = __builtin_amdgcn_mfma_f32_16x16x32_bf16(Bt[n][k], At[m][k], acc[ai][bj][m][n], 0, 0, 0); __builtin_amdgcn_s_setprio(0); } while (0)
; #define PG8_WAIT_V(n) asm volatile("s_waitcnt vmcnt(" #n ")" ::: "memory")
; #define PG8_WAIT_L(n) asm volatile("s_waitcnt lgkmcnt(" #n ")" ::: "memory")
; #define PG8_BAR __builtin_amdgcn_s_barrier()
; #define PG8_SCHED __builtin_amdgcn_sched_barrier(0)
; template <class Epi, class Sched, bool ALIGN_EPI = false, bool SP2 = false>
; __device__ __forceinline__ void gemm_phase(PG8_LAS unsigned char* lds, const Gemm g, const Sched& S, const Epi& E) {
;     ...
;             PG8_LDA(At, 1, 1); PG8_STAGE(PG8_SB(1, 0), b3, voffB); PG8_STAGE(PG8_SB(1, 1), b3 + hstep, voffB); PG8_STAGE(PG8_SA(1, 0), a3, voffA);
;             PG8_WAIT_V(8); PG8_WAIT_L(0); PG8_BAR; PG8_MMA(1, 0, At, B0); PG8_MMA(1, 1, At, B1); PG8_BAR; PG8_SCHED;
;     ...
;         if constexpr (ALIGN_EPI) { if (wr == 0) PG8_BAR; }
	s_add_i32 s30, s49, s33
	v_lshl_add_u64 v[156:157], v[156:157], 0, s[12:13]
	s_mov_b32 m0, s30
	ds_read_b128 v[192:195], v163 offset:49152
	ds_read_b128 v[196:199], v163 offset:50176
	ds_read_b128 v[200:203], v163 offset:51200
	ds_read_b128 v[204:207], v163 offset:52224
	ds_read_b128 v[208:211], v163 offset:53248
	ds_read_b128 v[212:215], v163 offset:54272
	ds_read_b128 v[216:219], v163 offset:55296
	ds_read_b128 v[220:223], v163 offset:56320
	global_load_lds_dwordx4 v[156:157], off
	s_add_i32 m0, s30, 0x2000
	s_add_u32 s28, s28, 0x80080
	v_lshl_add_u64 v[156:157], v[182:183], 0, s[12:13]
	s_addc_u32 s29, s29, 0
	s_add_i32 s30, s50, s33
	global_load_lds_dwordx4 v[156:157], off
	v_lshl_add_u64 v[156:157], s[28:29], 0, v[138:139]
	s_mov_b32 m0, s30
	s_nop 0
	global_load_lds_dwordx4 v[156:157], off
	v_lshl_add_u64 v[156:157], s[28:29], 0, v[142:143]
	s_add_i32 m0, s30, 0x2000
	s_nop 0
	global_load_lds_dwordx4 v[156:157], off
	v_lshl_add_u64 v[156:157], v[224:225], 0, s[12:13]
	s_mov_b32 m0, s38
	s_nop 0
	global_load_lds_dwordx4 v[156:157], off
	v_lshl_add_u64 v[156:157], v[226:227], 0, s[12:13]
	s_mov_b32 m0, s39
	s_nop 0
	global_load_lds_dwordx4 v[156:157], off
	s_waitcnt vmcnt(8)
	s_waitcnt lgkmcnt(0)
	s_barrier
	s_setprio 1
	s_waitcnt lgkmcnt(0)
	v_mfma_f32_16x16x32_bf16 v[60:63], v[128:131], v[192:195], v[60:63]
	v_mfma_f32_16x16x32_bf16 v[56:59], v[152:155], v[192:195], v[56:59]
	v_mfma_f32_16x16x32_bf16 v[44:47], v[128:131], v[200:203], v[44:47]
	v_mfma_f32_16x16x32_bf16 v[40:43], v[152:155], v[200:203], v[40:43]
	v_mfma_f32_16x16x32_bf16 v[28:31], v[128:131], v[208:211], v[28:31]
	v_mfma_f32_16x16x32_bf16 v[24:27], v[152:155], v[208:211], v[24:27]
	v_mfma_f32_16x16x32_bf16 v[12:15], v[128:131], v[216:219], v[12:15]
	v_mfma_f32_16x16x32_bf16 v[8:11], v[152:155], v[216:219], v[8:11]
	v_mfma_f32_16x16x32_bf16 v[60:63], v[132:135], v[196:199], v[60:63]
	v_mfma_f32_16x16x32_bf16 v[56:59], v[166:169], v[196:199], v[56:59]
	v_mfma_f32_16x16x32_bf16 v[44:47], v[132:135], v[204:207], v[44:47]
	v_mfma_f32_16x16x32_bf16 v[40:43], v[166:169], v[204:207], v[40:43]
	v_mfma_f32_16x16x32_bf16 v[28:31], v[132:135], v[212:215], v[28:31]
	v_mfma_f32_16x16x32_bf16 v[24:27], v[166:169], v[212:215], v[24:27]
	v_mfma_f32_16x16x32_bf16 v[12:15], v[132:135], v[220:223], v[12:15]
	v_mfma_f32_16x16x32_bf16 v[8:11], v[166:169], v[220:223], v[8:11]
	s_setprio 0
	s_setprio 1
	v_mfma_f32_16x16x32_bf16 v[52:55], v[170:173], v[192:195], v[52:55]
	v_mfma_f32_16x16x32_bf16 v[48:51], v[178:181], v[192:195], v[48:51]
	v_mfma_f32_16x16x32_bf16 v[36:39], v[170:173], v[200:203], v[36:39]
	v_mfma_f32_16x16x32_bf16 v[32:35], v[178:181], v[200:203], v[32:35]
	v_mfma_f32_16x16x32_bf16 v[20:23], v[170:173], v[208:211], v[20:23]
	v_mfma_f32_16x16x32_bf16 v[16:19], v[178:181], v[208:211], v[16:19]
	v_mfma_f32_16x16x32_bf16 v[4:7], v[170:173], v[216:219], v[4:7]
	v_mfma_f32_16x16x32_bf16 v[0:3], v[178:181], v[216:219], v[0:3]
	v_mfma_f32_16x16x32_bf16 v[52:55], v[174:177], v[196:199], v[52:55]
	v_mfma_f32_16x16x32_bf16 v[48:51], v[188:191], v[196:199], v[48:51]
	v_mfma_f32_16x16x32_bf16 v[36:39], v[174:177], v[204:207], v[36:39]
	v_mfma_f32_16x16x32_bf16 v[32:35], v[188:191], v[204:207], v[32:35]
	v_mfma_f32_16x16x32_bf16 v[20:23], v[174:177], v[212:215], v[20:23]
	v_mfma_f32_16x16x32_bf16 v[16:19], v[188:191], v[212:215], v[16:19]
	v_mfma_f32_16x16x32_bf16 v[4:7], v[174:177], v[220:223], v[4:7]
	v_mfma_f32_16x16x32_bf16 v[0:3], v[188:191], v[220:223], v[0:3]
	s_setprio 0
	s_add_i32 s48, s48, 2
	s_add_u32 s26, s26, 0x100
	s_addc_u32 s27, s27, 0
	s_add_u32 s46, s46, 0x100
	s_addc_u32 s47, s47, 0
	s_cmp_gt_u32 s48, 29
	s_barrier
	s_cbranch_scc0 .LBB0_964
	s_and_b64 vcc, exec, s[14:15]
	s_cbranch_vccz .LBB0_967
	s_barrier

; #define PG8_STAGE(bufoff, gbase, voff) do { _Pragma("unroll") for (int _i = 0; _i < 2; ++_i) \
;         __builtin_amdgcn_global_load_lds((const unsigned*)((const char*)(gbase) + (voff)[_i]), (PG8_LAS unsigned*)(lds + (bufoff) + ldsw + _i * 8192), 16, 0, 0); } while (0)
; #define PG8_LDA(dst, b, h) do { _Pragma("unroll") for (int m = 0; m < 4; ++m) _Pragma("unroll") for (int k = 0; k < 2; ++k) dst[m][k] = *(const PG8_LAS bf16x8*)(lds + PG8_SA(b, h) + aoff + m * 2048 + k * 1024); } while (0)
; #define PG8_LDB(dst, b, h) do { _Pragma("unroll") for (int n = 0; n < 2; ++n) _Pragma("unroll") for (int k = 0; k < 2; ++k) dst[n][k] = *(const PG8_LAS bf16x8*)(lds + PG8_SB(b, h) + boff + n * 2048 + k * 1024); } while (0)
; #define PG8_MMA(ai, bj, At, Bt) do { __builtin_amdgcn_s_setprio(1); _Pragma("unroll") for (int m = 0; m < 4; ++m) _Pragma("unroll") for (int n = 0; n < 2; ++n) _Pragma("unroll") for (int k = 0; k < 2; ++k) \
;         acc[ai][bj][m][n] = __builtin_amdgcn_mfma_f32_16x16x32_bf16(Bt[n][k], At[m][k], acc[ai][bj][m][n], 0, 0, 0); __builtin_amdgcn_s_setprio(0); } while (0)
; #define PG8_WAIT_V(n) asm volatile("s_waitcnt vmcnt(" #n ")" ::: "memory")
; #define PG8_WAIT_L(n) asm volatile("s_waitcnt lgkmcnt(" #n ")" ::: "memory")
; #define PG8_BAR __builtin_amdgcn_s_barrier()
; #define PG8_SCHED __builtin_amdgcn_sched_barrier(0)
; template <class Epi, class Sched, bool ALIGN_EPI = false, bool SP2 = false>
; __device__ __forceinline__ void gemm_phase(PG8_LAS unsigned char* lds, const Gemm g, const Sched& S, const Epi& E) {
;     ...
;             const bool last = (t == nt - 2);
;             const char* a1 = cA + (size_t)(t + 1) * kstep;
;             const char* a2 = last ? nA : cA + (size_t)(t + 2) * kstep; const char* b2 = last ? nB : cB + (size_t)(t + 2) * kstep;
;             const char* a3 = a2 + kstep; const char* b3 = b2 + kstep;
;             if (last && has_next) S.a_ready(nxt);
;             if constexpr (SP2) {
;             PG8_LDB(B0, 0, 0); PG8_LDB(B1, 0, 1); PG8_SCHED; PG8_LDA(At, 0, 0); PG8_STAGE(PG8_SA(1, 1), a1 + hstep, voffA);
;             PG8_WAIT_V(8); PG8_WAIT_L(0); PG8_BAR; PG8_MMA(0, 0, At, B0); PG8_MMA(0, 1, At, B1); PG8_BAR; PG8_SCHED;
;             PG8_LDA(At, 0, 1); PG8_STAGE(PG8_SB(0, 0), b2, voffB); PG8_STAGE(PG8_SB(0, 1), b2 + hstep, voffB); PG8_STAGE(PG8_SA(0, 0), a2, voffA);
.LBB0_1051:
	ds_read_b128 v[154:157], v150
	ds_read_b128 v[158:161], v150 offset:1024
	ds_read_b128 v[162:165], v150 offset:2048
	ds_read_b128 v[166:169], v150 offset:3072
	ds_read_b128 v[170:173], v151
	ds_read_b128 v[174:177], v151 offset:1024
	ds_read_b128 v[178:181], v151 offset:2048
	ds_read_b128 v[188:191], v151 offset:3072
	s_add_u32 s8, s2, 0xfff80080
	s_addc_u32 s9, s3, -1
	s_cmp_eq_u32 s18, 28
	s_cselect_b32 s11, s12, s9
	s_cselect_b32 s10, s13, s8
	s_cselect_b32 s9, s14, s17
	s_cselect_b32 s8, s15, s16
	v_lshl_add_u64 v[144:145], s[2:3], 0, v[136:137]
	s_add_i32 m0, s40, 0xc000
	ds_read_b128 v[192:195], v152
	ds_read_b128 v[196:199], v152 offset:1024
	ds_read_b128 v[200:203], v152 offset:2048
	ds_read_b128 v[204:207], v152 offset:3072
	ds_read_b128 v[208:211], v152 offset:4096
	ds_read_b128 v[212:215], v152 offset:5120
	ds_read_b128 v[216:219], v152 offset:6144
	ds_read_b128 v[220:223], v152 offset:7168
	global_load_lds_dwordx4 v[144:145], off
	v_lshl_add_u64 v[144:145], s[2:3], 0, v[138:139]
	s_add_i32 m0, s40, 0xe000
	s_nop 0
	global_load_lds_dwordx4 v[144:145], off
	s_waitcnt vmcnt(8)
	s_waitcnt lgkmcnt(0)
	s_barrier
	s_setprio 1
	s_waitcnt lgkmcnt(0)
	v_mfma_f32_16x16x32_bf16 v[116:119], v[154:157], v[192:195], v[116:119]
	v_mfma_f32_16x16x32_bf16 v[124:127], v[162:165], v[192:195], v[124:127]
	v_mfma_f32_16x16x32_bf16 v[112:115], v[154:157], v[200:203], v[112:115]
	v_mfma_f32_16x16x32_bf16 v[120:123], v[162:165], v[200:203], v[120:123]
	v_mfma_f32_16x16x32_bf16 v[84:87], v[154:157], v[208:211], v[84:87]
	v_mfma_f32_16x16x32_bf16 v[92:95], v[162:165], v[208:211], v[92:95]
	v_mfma_f32_16x16x32_bf16 v[80:83], v[154:157], v[216:219], v[80:83]
	v_mfma_f32_16x16x32_bf16 v[88:91], v[162:165], v[216:219], v[88:91]
	v_mfma_f32_16x16x32_bf16 v[116:119], v[158:161], v[196:199], v[116:119]
	v_mfma_f32_16x16x32_bf16 v[124:127], v[166:169], v[196:199], v[124:127]
	v_mfma_f32_16x16x32_bf16 v[112:115], v[158:161], v[204:207], v[112:115]
	v_mfma_f32_16x16x32_bf16 v[120:123], v[166:169], v[204:207], v[120:123]
	v_mfma_f32_16x16x32_bf16 v[84:87], v[158:161], v[212:215], v[84:87]
	v_mfma_f32_16x16x32_bf16 v[92:95], v[166:169], v[212:215], v[92:95]
	v_mfma_f32_16x16x32_bf16 v[80:83], v[158:161], v[220:223], v[80:83]
	v_mfma_f32_16x16x32_bf16 v[88:91], v[166:169], v[220:223], v[88:91]
	s_setprio 0
	s_setprio 1
	v_mfma_f32_16x16x32_bf16 v[100:103], v[170:173], v[192:195], v[100:103]
	v_mfma_f32_16x16x32_bf16 v[108:111], v[178:181], v[192:195], v[108:111]
	v_mfma_f32_16x16x32_bf16 v[96:99], v[170:173], v[200:203], v[96:99]
	v_mfma_f32_16x16x32_bf16 v[104:107], v[178:181], v[200:203], v[104:107]
	v_mfma_f32_16x16x32_bf16 v[68:71], v[170:173], v[208:211], v[68:71]
	v_mfma_f32_16x16x32_bf16 v[76:79], v[178:181], v[208:211], v[76:79]
	v_mfma_f32_16x16x32_bf16 v[64:67], v[170:173], v[216:219], v[64:67]
	v_mfma_f32_16x16x32_bf16 v[72:75], v[178:181], v[216:219], v[72:75]
	v_mfma_f32_16x16x32_bf16 v[100:103], v[174:177], v[196:199], v[100:103]
	v_mfma_f32_16x16x32_bf16 v[108:111], v[188:191], v[196:199], v[108:111]
	v_mfma_f32_16x16x32_bf16 v[96:99], v[174:177], v[204:207], v[96:99]
	v_mfma_f32_16x16x32_bf16 v[104:107], v[188:191], v[204:207], v[104:107]
	v_mfma_f32_16x16x32_bf16 v[68:71], v[174:177], v[212:215], v[68:71]
	v_mfma_f32_16x16x32_bf16 v[76:79], v[188:191], v[212:215], v[76:79]
	v_mfma_f32_16x16x32_bf16 v[64:67], v[174:177], v[220:223], v[64:67]
	v_mfma_f32_16x16x32_bf16 v[72:75], v[188:191], v[220:223], v[72:75]
	s_setprio 0
	s_barrier
	s_add_i32 s19, s50, s33
	v_lshl_add_u64 v[144:145], s[8:9], 0, v[132:133]
	s_mov_b32 m0, s19
	ds_read_b128 v[192:195], v152 offset:16384
	ds_read_b128 v[196:199], v152 offset:17408
	ds_read_b128 v[200:203], v152 offset:18432
	ds_read_b128 v[204:207], v152 offset:19456
	ds_read_b128 v[208:211], v152 offset:20480
	ds_read_b128 v[212:215], v152 offset:21504
	ds_read_b128 v[216:219], v152 offset:22528
	ds_read_b128 v[220:223], v152 offset:23552
	global_load_lds_dwordx4 v[144:145], off
	s_add_i32 m0, s19, 0x2000
	s_add_u32 s54, s8, 0x80000
	v_lshl_add_u64 v[182:183], s[8:9], 0, v[128:129]
	s_addc_u32 s55, s9, 0
	s_add_i32 s19, s51, s33
	global_load_lds_dwordx4 v[182:183], off
	v_lshl_add_u64 v[224:225], s[54:55], 0, v[132:133]
	s_mov_b32 m0, s19
	v_lshl_add_u64 v[226:227], s[10:11], 0, v[130:131]
	global_load_lds_dwordx4 v[224:225], off
	v_lshl_add_u64 v[224:225], s[54:55], 0, v[128:129]
	s_add_i32 m0, s19, 0x2000
	s_nop 0
	global_load_lds_dwordx4 v[224:225], off
	v_lshl_add_u64 v[224:225], s[10:11], 0, v[134:135]
	s_mov_b32 m0, s40
	s_nop 0
	global_load_lds_dwordx4 v[224:225], off
	s_mov_b32 m0, s41
	s_nop 0
	global_load_lds_dwordx4 v[226:227], off
	s_waitcnt vmcnt(8)
	s_waitcnt lgkmcnt(0)
	s_barrier
; #define PG8_STAGE(bufoff, gbase, voff) do { _Pragma("unroll") for (int _i = 0; _i < 2; ++_i) \
;         __builtin_amdgcn_global_load_lds((const unsigned*)((const char*)(gbase) + (voff)[_i]), (PG8_LAS unsigned*)(lds + (bufoff) + ldsw + _i * 8192), 16, 0, 0); } while (0)
; #define PG8_LDA(dst, b, h) do { _Pragma("unroll") for (int m = 0; m < 4; ++m) _Pragma("unroll") for (int k = 0; k < 2; ++k) dst[m][k] = *(const PG8_LAS bf16x8*)(lds + PG8_SA(b, h) + aoff + m * 2048 + k * 1024); } while (0)
; #define PG8_LDB(dst, b, h) do { _Pragma("unroll") for (int n = 0; n < 2; ++n) _Pragma("unroll") for (int k = 0; k < 2; ++k) dst[n][k] = *(const PG8_LAS bf16x8*)(lds + PG8_SB(b, h) + boff + n * 2048 + k * 1024); } while (0)
; #define PG8_MMA(ai, bj, At, Bt) do { __builtin_amdgcn_s_setprio(1); _Pragma("unroll") for (int m = 0; m < 4; ++m) _Pragma("unroll") for (int n = 0; n < 2; ++n) _Pragma("unroll") for (int k = 0; k < 2; ++k) \
;         acc[ai][bj][m][n] = __builtin_amdgcn_mfma_f32_16x16x32_bf16(Bt[n][k], At[m][k], acc[ai][bj][m][n], 0, 0, 0); __builtin_amdgcn_s_setprio(0); } while (0)
; #define PG8_WAIT_V(n) asm volatile("s_waitcnt vmcnt(" #n ")" ::: "memory")
; #define PG8_WAIT_L(n) asm volatile("s_waitcnt lgkmcnt(" #n ")" ::: "memory")
; #define PG8_BAR __builtin_amdgcn_s_barrier()
; #define PG8_SCHED __builtin_amdgcn_sched_barrier(0)
; template <class Epi, class Sched, bool ALIGN_EPI = false, bool SP2 = false>
; __device__ __forceinline__ void gemm_phase(PG8_LAS unsigned char* lds, const Gemm g, const Sched& S, const Epi& E) {
;     ...
;             PG8_WAIT_V(8); PG8_WAIT_L(0); PG8_BAR; PG8_MMA(1, 0, At, B0); PG8_MMA(1, 1, At, B1); PG8_BAR; PG8_SCHED;
;             PG8_LDB(B0, 1, 0); PG8_LDB(B1, 1, 1); PG8_SCHED; PG8_LDA(At, 1, 0); PG8_STAGE(PG8_SA(0, 1), a2 + hstep, voffA);
;             PG8_WAIT_V(8); PG8_WAIT_L(0); PG8_BAR; PG8_MMA(0, 0, At, B0); PG8_MMA(0, 1, At, B1); PG8_BAR; PG8_SCHED;
	s_setprio 1
	s_waitcnt lgkmcnt(0)
	v_mfma_f32_16x16x32_bf16 v[52:55], v[154:157], v[192:195], v[52:55]
	v_mfma_f32_16x16x32_bf16 v[60:63], v[162:165], v[192:195], v[60:63]
	v_mfma_f32_16x16x32_bf16 v[48:51], v[154:157], v[200:203], v[48:51]
	v_mfma_f32_16x16x32_bf16 v[56:59], v[162:165], v[200:203], v[56:59]
	v_mfma_f32_16x16x32_bf16 v[20:23], v[154:157], v[208:211], v[20:23]
	v_mfma_f32_16x16x32_bf16 v[28:31], v[162:165], v[208:211], v[28:31]
	v_mfma_f32_16x16x32_bf16 v[16:19], v[154:157], v[216:219], v[16:19]
	v_mfma_f32_16x16x32_bf16 v[24:27], v[162:165], v[216:219], v[24:27]
	v_mfma_f32_16x16x32_bf16 v[52:55], v[158:161], v[196:199], v[52:55]
	v_mfma_f32_16x16x32_bf16 v[60:63], v[166:169], v[196:199], v[60:63]
	v_mfma_f32_16x16x32_bf16 v[48:51], v[158:161], v[204:207], v[48:51]
	v_mfma_f32_16x16x32_bf16 v[56:59], v[166:169], v[204:207], v[56:59]
	v_mfma_f32_16x16x32_bf16 v[20:23], v[158:161], v[212:215], v[20:23]
	v_mfma_f32_16x16x32_bf16 v[28:31], v[166:169], v[212:215], v[28:31]
	v_mfma_f32_16x16x32_bf16 v[16:19], v[158:161], v[220:223], v[16:19]
	v_mfma_f32_16x16x32_bf16 v[24:27], v[166:169], v[220:223], v[24:27]
	s_setprio 0
	s_setprio 1
	v_mfma_f32_16x16x32_bf16 v[36:39], v[170:173], v[192:195], v[36:39]
	v_mfma_f32_16x16x32_bf16 v[44:47], v[178:181], v[192:195], v[44:47]
	v_mfma_f32_16x16x32_bf16 v[32:35], v[170:173], v[200:203], v[32:35]
	v_mfma_f32_16x16x32_bf16 v[40:43], v[178:181], v[200:203], v[40:43]
	v_mfma_f32_16x16x32_bf16 v[8:11], v[170:173], v[208:211], v[8:11]
	v_mfma_f32_16x16x32_bf16 v[12:15], v[178:181], v[208:211], v[12:15]
	v_mfma_f32_16x16x32_bf16 v[0:3], v[170:173], v[216:219], v[0:3]
	v_mfma_f32_16x16x32_bf16 v[4:7], v[178:181], v[216:219], v[4:7]
	v_mfma_f32_16x16x32_bf16 v[36:39], v[174:177], v[196:199], v[36:39]
	v_mfma_f32_16x16x32_bf16 v[44:47], v[188:191], v[196:199], v[44:47]
	v_mfma_f32_16x16x32_bf16 v[32:35], v[174:177], v[204:207], v[32:35]
	v_mfma_f32_16x16x32_bf16 v[40:43], v[188:191], v[204:207], v[40:43]
	v_mfma_f32_16x16x32_bf16 v[8:11], v[174:177], v[212:215], v[8:11]
	v_mfma_f32_16x16x32_bf16 v[12:15], v[188:191], v[212:215], v[12:15]
	v_mfma_f32_16x16x32_bf16 v[0:3], v[174:177], v[220:223], v[0:3]
	v_mfma_f32_16x16x32_bf16 v[4:7], v[188:191], v[220:223], v[4:7]
	s_setprio 0
	s_barrier
	s_add_i32 s19, 0, 0x18000
	s_add_i32 s29, 0, 0x1c000
	v_add_u32_e32 v166, s19, v147
	v_add_u32_e32 v185, s29, v147
	ds_read_b128 v[154:157], v166
	ds_read_b128 v[158:161], v166 offset:1024
	ds_read_b128 v[162:165], v166 offset:2048
	ds_read_b128 v[166:169], v166 offset:3072
	ds_read_b128 v[170:173], v185
	ds_read_b128 v[174:177], v185 offset:1024
	ds_read_b128 v[178:181], v185 offset:2048
	ds_read_b128 v[188:191], v185 offset:3072
	s_add_u32 s10, s10, 0x80000
	s_addc_u32 s11, s11, 0
	s_mov_b32 m0, s42
	v_lshl_add_u64 v[228:229], s[10:11], 0, v[134:135]
	ds_read_b128 v[192:195], v152 offset:32768
	ds_read_b128 v[196:199], v152 offset:33792
	ds_read_b128 v[200:203], v152 offset:34816
	ds_read_b128 v[204:207], v152 offset:35840
	ds_read_b128 v[208:211], v152 offset:36864
	ds_read_b128 v[212:215], v152 offset:37888
	ds_read_b128 v[216:219], v152 offset:38912
	ds_read_b128 v[220:223], v152 offset:39936
	global_load_lds_dwordx4 v[228:229], off
	v_lshl_add_u64 v[228:229], s[10:11], 0, v[130:131]
	s_mov_b32 m0, s43
	s_nop 0
	global_load_lds_dwordx4 v[228:229], off
	s_waitcnt vmcnt(8)
	s_waitcnt lgkmcnt(0)
	s_barrier
	s_setprio 1
	s_waitcnt lgkmcnt(0)
	v_mfma_f32_16x16x32_bf16 v[116:119], v[154:157], v[192:195], v[116:119]
	v_mfma_f32_16x16x32_bf16 v[124:127], v[162:165], v[192:195], v[124:127]
	v_mfma_f32_16x16x32_bf16 v[112:115], v[154:157], v[200:203], v[112:115]
	v_mfma_f32_16x16x32_bf16 v[120:123], v[162:165], v[200:203], v[120:123]
	v_mfma_f32_16x16x32_bf16 v[84:87], v[154:157], v[208:211], v[84:87]
	v_mfma_f32_16x16x32_bf16 v[92:95], v[162:165], v[208:211], v[92:95]
	v_mfma_f32_16x16x32_bf16 v[80:83], v[154:157], v[216:219], v[80:83]
	v_mfma_f32_16x16x32_bf16 v[88:91], v[162:165], v[216:219], v[88:91]
	v_mfma_f32_16x16x32_bf16 v[116:119], v[158:161], v[196:199], v[116:119]
	v_mfma_f32_16x16x32_bf16 v[124:127], v[166:169], v[196:199], v[124:127]
	v_mfma_f32_16x16x32_bf16 v[112:115], v[158:161], v[204:207], v[112:115]
	v_mfma_f32_16x16x32_bf16 v[120:123], v[166:169], v[204:207], v[120:123]
	v_mfma_f32_16x16x32_bf16 v[84:87], v[158:161], v[212:215], v[84:87]
	v_mfma_f32_16x16x32_bf16 v[92:95], v[166:169], v[212:215], v[92:95]
	v_mfma_f32_16x16x32_bf16 v[80:83], v[158:161], v[220:223], v[80:83]
	v_mfma_f32_16x16x32_bf16 v[88:91], v[166:169], v[220:223], v[88:91]
	s_setprio 0
	s_setprio 1
	v_mfma_f32_16x16x32_bf16 v[100:103], v[170:173], v[192:195], v[100:103]
	v_mfma_f32_16x16x32_bf16 v[108:111], v[178:181], v[192:195], v[108:111]
	v_mfma_f32_16x16x32_bf16 v[96:99], v[170:173], v[200:203], v[96:99]
	v_mfma_f32_16x16x32_bf16 v[104:107], v[178:181], v[200:203], v[104:107]
	v_mfma_f32_16x16x32_bf16 v[68:71], v[170:173], v[208:211], v[68:71]
	v_mfma_f32_16x16x32_bf16 v[76:79], v[178:181], v[208:211], v[76:79]
	v_mfma_f32_16x16x32_bf16 v[64:67], v[170:173], v[216:219], v[64:67]
	v_mfma_f32_16x16x32_bf16 v[72:75], v[178:181], v[216:219], v[72:75]
	v_mfma_f32_16x16x32_bf16 v[100:103], v[174:177], v[196:199], v[100:103]
	v_mfma_f32_16x16x32_bf16 v[108:111], v[188:191], v[196:199], v[108:111]
	v_mfma_f32_16x16x32_bf16 v[96:99], v[174:177], v[204:207], v[96:99]
	v_mfma_f32_16x16x32_bf16 v[104:107], v[188:191], v[204:207], v[104:107]
	v_mfma_f32_16x16x32_bf16 v[68:71], v[174:177], v[212:215], v[68:71]
	v_mfma_f32_16x16x32_bf16 v[76:79], v[188:191], v[212:215], v[76:79]
	v_mfma_f32_16x16x32_bf16 v[64:67], v[174:177], v[220:223], v[64:67]
	v_mfma_f32_16x16x32_bf16 v[72:75], v[188:191], v[220:223], v[72:75]
	s_setprio 0
	s_barrier
; #define PG8_STAGE(bufoff, gbase, voff) do { _Pragma("unroll") for (int _i = 0; _i < 2; ++_i) \
;         __builtin_amdgcn_global_load_lds((const unsigned*)((const char*)(gbase) + (voff)[_i]), (PG8_LAS unsigned*)(lds + (bufoff) + ldsw + _i * 8192), 16, 0, 0); } while (0)
; #define PG8_LDA(dst, b, h) do { _Pragma("unroll") for (int m = 0; m < 4; ++m) _Pragma("unroll") for (int k = 0; k < 2; ++k) dst[m][k] = *(const PG8_LAS bf16x8*)(lds + PG8_SA(b, h) + aoff + m * 2048 + k * 1024); } while (0)
; #define PG8_MMA(ai, bj, At, Bt) do { __builtin_amdgcn_s_setprio(1); _Pragma("unroll") for (int m = 0; m < 4; ++m) _Pragma("unroll") for (int n = 0; n < 2; ++n) _Pragma("unroll") for (int k = 0; k < 2; ++k) \
;         acc[ai][bj][m][n] = __builtin_amdgcn_mfma_f32_16x16x32_bf16(Bt[n][k], At[m][k], acc[ai][bj][m][n], 0, 0, 0); __builtin_amdgcn_s_setprio(0); } while (0)
; #define PG8_WAIT_V(n) asm volatile("s_waitcnt vmcnt(" #n ")" ::: "memory")
; #define PG8_WAIT_L(n) asm volatile("s_waitcnt lgkmcnt(" #n ")" ::: "memory")
; #define PG8_BAR __builtin_amdgcn_s_barrier()
; #define PG8_SCHED __builtin_amdgcn_sched_barrier(0)
; template <class Epi, class Sched, bool ALIGN_EPI = false, bool SP2 = false>
; __device__ __forceinline__ void gemm_phase(PG8_LAS unsigned char* lds, const Gemm g, const Sched& S, const Epi& E) {
;     ...
;             PG8_LDA(At, 1, 1); PG8_STAGE(PG8_SB(1, 0), b3, voffB); PG8_STAGE(PG8_SB(1, 1), b3 + hstep, voffB); PG8_STAGE(PG8_SA(1, 0), a3, voffA);
;             PG8_WAIT_V(8); PG8_WAIT_L(0); PG8_BAR; PG8_MMA(1, 0, At, B0); PG8_MMA(1, 1, At, B1); PG8_BAR; PG8_SCHED;
;     ...
;         if constexpr (ALIGN_EPI) { if (wr == 0) PG8_BAR; }
	s_add_i32 s10, s19, s33
	v_lshl_add_u64 v[144:145], v[144:145], 0, s[24:25]
	s_mov_b32 m0, s10
	ds_read_b128 v[192:195], v152 offset:49152
	ds_read_b128 v[196:199], v152 offset:50176
	ds_read_b128 v[200:203], v152 offset:51200
	ds_read_b128 v[204:207], v152 offset:52224
	ds_read_b128 v[208:211], v152 offset:53248
	ds_read_b128 v[212:215], v152 offset:54272
	ds_read_b128 v[216:219], v152 offset:55296
	ds_read_b128 v[220:223], v152 offset:56320
	global_load_lds_dwordx4 v[144:145], off
	s_add_i32 m0, s10, 0x2000
	s_add_u32 s8, s8, 0x80080
	v_lshl_add_u64 v[144:145], v[182:183], 0, s[24:25]
	s_addc_u32 s9, s9, 0
	s_add_i32 s10, s29, s33
	global_load_lds_dwordx4 v[144:145], off
	v_lshl_add_u64 v[144:145], s[8:9], 0, v[132:133]
	s_mov_b32 m0, s10
	s_nop 0
	global_load_lds_dwordx4 v[144:145], off
	v_lshl_add_u64 v[144:145], s[8:9], 0, v[128:129]
	s_add_i32 m0, s10, 0x2000
	s_nop 0
	global_load_lds_dwordx4 v[144:145], off
	v_lshl_add_u64 v[144:145], v[224:225], 0, s[24:25]
	s_mov_b32 m0, s46
	s_nop 0
	global_load_lds_dwordx4 v[144:145], off
	v_lshl_add_u64 v[144:145], v[226:227], 0, s[24:25]
	s_mov_b32 m0, s47
	s_nop 0
	global_load_lds_dwordx4 v[144:145], off
	s_waitcnt vmcnt(8)
	s_waitcnt lgkmcnt(0)
	s_barrier
	s_setprio 1
	s_waitcnt lgkmcnt(0)
	v_mfma_f32_16x16x32_bf16 v[52:55], v[154:157], v[192:195], v[52:55]
	v_mfma_f32_16x16x32_bf16 v[60:63], v[162:165], v[192:195], v[60:63]
	v_mfma_f32_16x16x32_bf16 v[48:51], v[154:157], v[200:203], v[48:51]
	v_mfma_f32_16x16x32_bf16 v[56:59], v[162:165], v[200:203], v[56:59]
	v_mfma_f32_16x16x32_bf16 v[20:23], v[154:157], v[208:211], v[20:23]
	v_mfma_f32_16x16x32_bf16 v[28:31], v[162:165], v[208:211], v[28:31]
	v_mfma_f32_16x16x32_bf16 v[16:19], v[154:157], v[216:219], v[16:19]
	v_mfma_f32_16x16x32_bf16 v[24:27], v[162:165], v[216:219], v[24:27]
	v_mfma_f32_16x16x32_bf16 v[52:55], v[158:161], v[196:199], v[52:55]
	v_mfma_f32_16x16x32_bf16 v[60:63], v[166:169], v[196:199], v[60:63]
	v_mfma_f32_16x16x32_bf16 v[48:51], v[158:161], v[204:207], v[48:51]
	v_mfma_f32_16x16x32_bf16 v[56:59], v[166:169], v[204:207], v[56:59]
	v_mfma_f32_16x16x32_bf16 v[20:23], v[158:161], v[212:215], v[20:23]
	v_mfma_f32_16x16x32_bf16 v[28:31], v[166:169], v[212:215], v[28:31]
	v_mfma_f32_16x16x32_bf16 v[16:19], v[158:161], v[220:223], v[16:19]
	v_mfma_f32_16x16x32_bf16 v[24:27], v[166:169], v[220:223], v[24:27]
	s_setprio 0
	s_setprio 1
	v_mfma_f32_16x16x32_bf16 v[36:39], v[170:173], v[192:195], v[36:39]
	v_mfma_f32_16x16x32_bf16 v[44:47], v[178:181], v[192:195], v[44:47]
	v_mfma_f32_16x16x32_bf16 v[32:35], v[170:173], v[200:203], v[32:35]
	v_mfma_f32_16x16x32_bf16 v[40:43], v[178:181], v[200:203], v[40:43]
	v_mfma_f32_16x16x32_bf16 v[8:11], v[170:173], v[208:211], v[8:11]
	v_mfma_f32_16x16x32_bf16 v[12:15], v[178:181], v[208:211], v[12:15]
	v_mfma_f32_16x16x32_bf16 v[0:3], v[170:173], v[216:219], v[0:3]
	v_mfma_f32_16x16x32_bf16 v[4:7], v[178:181], v[216:219], v[4:7]
	v_mfma_f32_16x16x32_bf16 v[36:39], v[174:177], v[196:199], v[36:39]
	v_mfma_f32_16x16x32_bf16 v[44:47], v[188:191], v[196:199], v[44:47]
	v_mfma_f32_16x16x32_bf16 v[32:35], v[174:177], v[204:207], v[32:35]
	v_mfma_f32_16x16x32_bf16 v[40:43], v[188:191], v[204:207], v[40:43]
	v_mfma_f32_16x16x32_bf16 v[8:11], v[174:177], v[212:215], v[8:11]
	v_mfma_f32_16x16x32_bf16 v[12:15], v[188:191], v[212:215], v[12:15]
	v_mfma_f32_16x16x32_bf16 v[0:3], v[174:177], v[220:223], v[0:3]
	v_mfma_f32_16x16x32_bf16 v[4:7], v[188:191], v[220:223], v[4:7]
	s_setprio 0
	s_add_i32 s18, s18, 2
	s_add_u32 s2, s2, 0x100
	s_addc_u32 s3, s3, 0
	s_add_u32 s16, s16, 0x100
	s_addc_u32 s17, s17, 0
	s_cmp_gt_u32 s18, 29
	s_barrier
	s_cbranch_scc0 .LBB0_1051
	s_and_b64 vcc, exec, s[26:27]
	s_cbranch_vccz .LBB0_1054
	s_barrier

; #define PG8_STAGE(bufoff, gbase, voff) do { _Pragma("unroll") for (int _i = 0; _i < 2; ++_i) \
;         __builtin_amdgcn_global_load_lds((const unsigned*)((const char*)(gbase) + (voff)[_i]), (PG8_LAS unsigned*)(lds + (bufoff) + ldsw + _i * 8192), 16, 0, 0); } while (0)
; #define PG8_LDA(dst, b, h) do { _Pragma("unroll") for (int m = 0; m < 4; ++m) _Pragma("unroll") for (int k = 0; k < 2; ++k) dst[m][k] = *(const PG8_LAS bf16x8*)(lds + PG8_SA(b, h) + aoff + m * 2048 + k * 1024); } while (0)
; #define PG8_LDB(dst, b, h) do { _Pragma("unroll") for (int n = 0; n < 2; ++n) _Pragma("unroll") for (int k = 0; k < 2; ++k) dst[n][k] = *(const PG8_LAS bf16x8*)(lds + PG8_SB(b, h) + boff + n * 2048 + k * 1024); } while (0)
; #define PG8_MMA(ai, bj, At, Bt) do { __builtin_amdgcn_s_setprio(1); _Pragma("unroll") for (int m = 0; m < 4; ++m) _Pragma("unroll") for (int n = 0; n < 2; ++n) _Pragma("unroll") for (int k = 0; k < 2; ++k) \
;         acc[ai][bj][m][n] = __builtin_amdgcn_mfma_f32_16x16x32_bf16(Bt[n][k], At[m][k], acc[ai][bj][m][n], 0, 0, 0); __builtin_amdgcn_s_setprio(0); } while (0)
; #define PG8_WAIT_V(n) asm volatile("s_waitcnt vmcnt(" #n ")" ::: "memory")
; #define PG8_WAIT_L(n) asm volatile("s_waitcnt lgkmcnt(" #n ")" ::: "memory")
; #define PG8_BAR __builtin_amdgcn_s_barrier()
; #define PG8_SCHED __builtin_amdgcn_sched_barrier(0)
; template <class Epi, class Sched, bool ALIGN_EPI = false, bool SP2 = false>
; __device__ __forceinline__ void gemm_phase(PG8_LAS unsigned char* lds, const Gemm g, const Sched& S, const Epi& E) {
;     ...
;             const bool last = (t == nt - 2);
;             const char* a1 = cA + (size_t)(t + 1) * kstep;
;             const char* a2 = last ? nA : cA + (size_t)(t + 2) * kstep; const char* b2 = last ? nB : cB + (size_t)(t + 2) * kstep;
;             const char* a3 = a2 + kstep; const char* b3 = b2 + kstep;
;             if (last && has_next) S.a_ready(nxt);
;             if constexpr (SP2) {
;             PG8_LDB(B0, 0, 0); PG8_LDB(B1, 0, 1); PG8_SCHED; PG8_LDA(At, 0, 0); PG8_STAGE(PG8_SA(1, 1), a1 + hstep, voffA);
;             PG8_WAIT_V(8); PG8_WAIT_L(0); PG8_BAR; PG8_MMA(0, 0, At, B0); PG8_MMA(0, 1, At, B1); PG8_BAR; PG8_SCHED;
;             PG8_LDA(At, 0, 1); PG8_STAGE(PG8_SB(0, 0), b2, voffB); PG8_STAGE(PG8_SB(0, 1), b2 + hstep, voffB); PG8_STAGE(PG8_SA(0, 0), a2, voffA);
.LBB0_1124:
	ds_read_b128 v[128:131], v188
	ds_read_b128 v[132:135], v188 offset:1024
	ds_read_b128 v[154:157], v188 offset:2048
	ds_read_b128 v[158:161], v188 offset:3072
	ds_read_b128 v[162:165], v189
	ds_read_b128 v[166:169], v189 offset:1024
	ds_read_b128 v[170:173], v189 offset:2048
	ds_read_b128 v[174:177], v189 offset:3072
	s_add_u32 s2, s0, 0xffea0080
	s_addc_u32 s3, s1, -1
	s_cmpk_eq_i32 s51, 0x54
	s_cselect_b32 s11, s27, s3
	s_cselect_b32 s10, s26, s2
	s_cselect_b32 s3, s31, s35
	s_cselect_b32 s2, s30, s34
	v_lshl_add_u64 v[182:183], s[0:1], 0, v[146:147]
	s_add_i32 m0, s25, 0xc000
	ds_read_b128 v[178:181], v190
	ds_read_b128 v[192:195], v190 offset:1024
	ds_read_b128 v[196:199], v190 offset:2048
	ds_read_b128 v[200:203], v190 offset:3072
	ds_read_b128 v[204:207], v190 offset:4096
	ds_read_b128 v[208:211], v190 offset:5120
	ds_read_b128 v[212:215], v190 offset:6144
	ds_read_b128 v[216:219], v190 offset:7168
	global_load_lds_dwordx4 v[182:183], off
	v_lshl_add_u64 v[182:183], s[0:1], 0, v[148:149]
	s_add_i32 m0, s25, 0xe000
	s_nop 0
	global_load_lds_dwordx4 v[182:183], off
	s_waitcnt vmcnt(8)
	s_waitcnt lgkmcnt(0)
	s_barrier
	s_setprio 1
	s_waitcnt lgkmcnt(0)
	v_mfma_f32_16x16x32_bf16 v[124:127], v[128:131], v[178:181], v[124:127]
	v_mfma_f32_16x16x32_bf16 v[120:123], v[154:157], v[178:181], v[120:123]
	v_mfma_f32_16x16x32_bf16 v[108:111], v[128:131], v[196:199], v[108:111]
	v_mfma_f32_16x16x32_bf16 v[104:107], v[154:157], v[196:199], v[104:107]
	v_mfma_f32_16x16x32_bf16 v[92:95], v[128:131], v[204:207], v[92:95]
	v_mfma_f32_16x16x32_bf16 v[88:91], v[154:157], v[204:207], v[88:91]
	v_mfma_f32_16x16x32_bf16 v[76:79], v[128:131], v[212:215], v[76:79]
	v_mfma_f32_16x16x32_bf16 v[72:75], v[154:157], v[212:215], v[72:75]
	v_mfma_f32_16x16x32_bf16 v[124:127], v[132:135], v[192:195], v[124:127]
	v_mfma_f32_16x16x32_bf16 v[120:123], v[158:161], v[192:195], v[120:123]
	v_mfma_f32_16x16x32_bf16 v[108:111], v[132:135], v[200:203], v[108:111]
	v_mfma_f32_16x16x32_bf16 v[104:107], v[158:161], v[200:203], v[104:107]
	v_mfma_f32_16x16x32_bf16 v[92:95], v[132:135], v[208:211], v[92:95]
	v_mfma_f32_16x16x32_bf16 v[88:91], v[158:161], v[208:211], v[88:91]
	v_mfma_f32_16x16x32_bf16 v[76:79], v[132:135], v[216:219], v[76:79]
	v_mfma_f32_16x16x32_bf16 v[72:75], v[158:161], v[216:219], v[72:75]
	s_setprio 0
	s_setprio 1
	v_mfma_f32_16x16x32_bf16 v[116:119], v[162:165], v[178:181], v[116:119]
	v_mfma_f32_16x16x32_bf16 v[112:115], v[170:173], v[178:181], v[112:115]
	v_mfma_f32_16x16x32_bf16 v[100:103], v[162:165], v[196:199], v[100:103]
	v_mfma_f32_16x16x32_bf16 v[96:99], v[170:173], v[196:199], v[96:99]
	v_mfma_f32_16x16x32_bf16 v[84:87], v[162:165], v[204:207], v[84:87]
	v_mfma_f32_16x16x32_bf16 v[80:83], v[170:173], v[204:207], v[80:83]
	v_mfma_f32_16x16x32_bf16 v[68:71], v[162:165], v[212:215], v[68:71]
	v_mfma_f32_16x16x32_bf16 v[64:67], v[170:173], v[212:215], v[64:67]
	v_mfma_f32_16x16x32_bf16 v[116:119], v[166:169], v[192:195], v[116:119]
	v_mfma_f32_16x16x32_bf16 v[112:115], v[174:177], v[192:195], v[112:115]
	v_mfma_f32_16x16x32_bf16 v[100:103], v[166:169], v[200:203], v[100:103]
	v_mfma_f32_16x16x32_bf16 v[96:99], v[174:177], v[200:203], v[96:99]
	v_mfma_f32_16x16x32_bf16 v[84:87], v[166:169], v[208:211], v[84:87]
	v_mfma_f32_16x16x32_bf16 v[80:83], v[174:177], v[208:211], v[80:83]
	v_mfma_f32_16x16x32_bf16 v[68:71], v[166:169], v[216:219], v[68:71]
	v_mfma_f32_16x16x32_bf16 v[64:67], v[174:177], v[216:219], v[64:67]
	s_setprio 0
	s_barrier
	s_add_i32 s52, s46, s23
	v_lshl_add_u64 v[182:183], s[2:3], 0, v[140:141]
	s_mov_b32 m0, s52
	ds_read_b128 v[178:181], v190 offset:16384
	ds_read_b128 v[192:195], v190 offset:17408
	ds_read_b128 v[196:199], v190 offset:18432
	ds_read_b128 v[200:203], v190 offset:19456
	ds_read_b128 v[204:207], v190 offset:20480
	ds_read_b128 v[208:211], v190 offset:21504
	ds_read_b128 v[212:215], v190 offset:22528
	ds_read_b128 v[216:219], v190 offset:23552
	global_load_lds_dwordx4 v[182:183], off
	s_add_i32 m0, s52, 0x2000
	s_add_u32 s52, s2, 0x160000
	v_lshl_add_u64 v[220:221], s[2:3], 0, v[136:137]
	s_addc_u32 s53, s3, 0
	s_add_i32 s54, s47, s23
	global_load_lds_dwordx4 v[220:221], off
	v_lshl_add_u64 v[222:223], s[52:53], 0, v[140:141]
	s_mov_b32 m0, s54
	v_lshl_add_u64 v[224:225], s[10:11], 0, v[138:139]
	global_load_lds_dwordx4 v[222:223], off
	v_lshl_add_u64 v[222:223], s[52:53], 0, v[136:137]
	s_add_i32 m0, s54, 0x2000
	s_nop 0
	global_load_lds_dwordx4 v[222:223], off
	v_lshl_add_u64 v[222:223], s[10:11], 0, v[142:143]
	s_mov_b32 m0, s25
	s_nop 0
	global_load_lds_dwordx4 v[222:223], off
	s_mov_b32 m0, s33
	s_nop 0
	global_load_lds_dwordx4 v[224:225], off
	s_waitcnt vmcnt(8)
	s_waitcnt lgkmcnt(0)
	s_barrier
; #define PG8_STAGE(bufoff, gbase, voff) do { _Pragma("unroll") for (int _i = 0; _i < 2; ++_i) \
;         __builtin_amdgcn_global_load_lds((const unsigned*)((const char*)(gbase) + (voff)[_i]), (PG8_LAS unsigned*)(lds + (bufoff) + ldsw + _i * 8192), 16, 0, 0); } while (0)
; #define PG8_LDA(dst, b, h) do { _Pragma("unroll") for (int m = 0; m < 4; ++m) _Pragma("unroll") for (int k = 0; k < 2; ++k) dst[m][k] = *(const PG8_LAS bf16x8*)(lds + PG8_SA(b, h) + aoff + m * 2048 + k * 1024); } while (0)
; #define PG8_LDB(dst, b, h) do { _Pragma("unroll") for (int n = 0; n < 2; ++n) _Pragma("unroll") for (int k = 0; k < 2; ++k) dst[n][k] = *(const PG8_LAS bf16x8*)(lds + PG8_SB(b, h) + boff + n * 2048 + k * 1024); } while (0)
; #define PG8_MMA(ai, bj, At, Bt) do { __builtin_amdgcn_s_setprio(1); _Pragma("unroll") for (int m = 0; m < 4; ++m) _Pragma("unroll") for (int n = 0; n < 2; ++n) _Pragma("unroll") for (int k = 0; k < 2; ++k) \
;         acc[ai][bj][m][n] = __builtin_amdgcn_mfma_f32_16x16x32_bf16(Bt[n][k], At[m][k], acc[ai][bj][m][n], 0, 0, 0); __builtin_amdgcn_s_setprio(0); } while (0)
; #define PG8_WAIT_V(n) asm volatile("s_waitcnt vmcnt(" #n ")" ::: "memory")
; #define PG8_WAIT_L(n) asm volatile("s_waitcnt lgkmcnt(" #n ")" ::: "memory")
; #define PG8_BAR __builtin_amdgcn_s_barrier()
; #define PG8_SCHED __builtin_amdgcn_sched_barrier(0)
; template <class Epi, class Sched, bool ALIGN_EPI = false, bool SP2 = false>
; __device__ __forceinline__ void gemm_phase(PG8_LAS unsigned char* lds, const Gemm g, const Sched& S, const Epi& E) {
;     ...
;             PG8_WAIT_V(8); PG8_WAIT_L(0); PG8_BAR; PG8_MMA(1, 0, At, B0); PG8_MMA(1, 1, At, B1); PG8_BAR; PG8_SCHED;
;             PG8_LDB(B0, 1, 0); PG8_LDB(B1, 1, 1); PG8_SCHED; PG8_LDA(At, 1, 0); PG8_STAGE(PG8_SA(0, 1), a2 + hstep, voffA);
;             PG8_WAIT_V(8); PG8_WAIT_L(0); PG8_BAR; PG8_MMA(0, 0, At, B0); PG8_MMA(0, 1, At, B1); PG8_BAR; PG8_SCHED;
	s_setprio 1
	s_waitcnt lgkmcnt(0)
	v_mfma_f32_16x16x32_bf16 v[60:63], v[128:131], v[178:181], v[60:63]
	v_mfma_f32_16x16x32_bf16 v[56:59], v[154:157], v[178:181], v[56:59]
	v_mfma_f32_16x16x32_bf16 v[44:47], v[128:131], v[196:199], v[44:47]
	v_mfma_f32_16x16x32_bf16 v[40:43], v[154:157], v[196:199], v[40:43]
	v_mfma_f32_16x16x32_bf16 v[28:31], v[128:131], v[204:207], v[28:31]
	v_mfma_f32_16x16x32_bf16 v[24:27], v[154:157], v[204:207], v[24:27]
	v_mfma_f32_16x16x32_bf16 v[12:15], v[128:131], v[212:215], v[12:15]
	v_mfma_f32_16x16x32_bf16 v[8:11], v[154:157], v[212:215], v[8:11]
	v_mfma_f32_16x16x32_bf16 v[60:63], v[132:135], v[192:195], v[60:63]
	v_mfma_f32_16x16x32_bf16 v[56:59], v[158:161], v[192:195], v[56:59]
	v_mfma_f32_16x16x32_bf16 v[44:47], v[132:135], v[200:203], v[44:47]
	v_mfma_f32_16x16x32_bf16 v[40:43], v[158:161], v[200:203], v[40:43]
	v_mfma_f32_16x16x32_bf16 v[28:31], v[132:135], v[208:211], v[28:31]
	v_mfma_f32_16x16x32_bf16 v[24:27], v[158:161], v[208:211], v[24:27]
	v_mfma_f32_16x16x32_bf16 v[12:15], v[132:135], v[216:219], v[12:15]
	v_mfma_f32_16x16x32_bf16 v[8:11], v[158:161], v[216:219], v[8:11]
	s_setprio 0
	s_setprio 1
	v_mfma_f32_16x16x32_bf16 v[52:55], v[162:165], v[178:181], v[52:55]
	v_mfma_f32_16x16x32_bf16 v[48:51], v[170:173], v[178:181], v[48:51]
	v_mfma_f32_16x16x32_bf16 v[36:39], v[162:165], v[196:199], v[36:39]
	v_mfma_f32_16x16x32_bf16 v[32:35], v[170:173], v[196:199], v[32:35]
	v_mfma_f32_16x16x32_bf16 v[20:23], v[162:165], v[204:207], v[20:23]
	v_mfma_f32_16x16x32_bf16 v[16:19], v[170:173], v[204:207], v[16:19]
	v_mfma_f32_16x16x32_bf16 v[4:7], v[162:165], v[212:215], v[4:7]
	v_mfma_f32_16x16x32_bf16 v[0:3], v[170:173], v[212:215], v[0:3]
	v_mfma_f32_16x16x32_bf16 v[52:55], v[166:169], v[192:195], v[52:55]
	v_mfma_f32_16x16x32_bf16 v[48:51], v[174:177], v[192:195], v[48:51]
	v_mfma_f32_16x16x32_bf16 v[36:39], v[166:169], v[200:203], v[36:39]
	v_mfma_f32_16x16x32_bf16 v[32:35], v[174:177], v[200:203], v[32:35]
	v_mfma_f32_16x16x32_bf16 v[20:23], v[166:169], v[208:211], v[20:23]
	v_mfma_f32_16x16x32_bf16 v[16:19], v[174:177], v[208:211], v[16:19]
	v_mfma_f32_16x16x32_bf16 v[4:7], v[166:169], v[216:219], v[4:7]
	v_mfma_f32_16x16x32_bf16 v[0:3], v[174:177], v[216:219], v[0:3]
	s_setprio 0
	s_barrier
	s_add_i32 s52, 0, 0x18000
	v_add_u32_e32 v144, s52, v186
	s_add_i32 s53, 0, 0x1c000
	ds_read_b128 v[128:131], v144
	ds_read_b128 v[132:135], v144 offset:1024
	ds_read_b128 v[154:157], v144 offset:2048
	ds_read_b128 v[158:161], v144 offset:3072
	v_add_u32_e32 v144, s53, v186
	ds_read_b128 v[162:165], v144
	ds_read_b128 v[166:169], v144 offset:1024
	ds_read_b128 v[170:173], v144 offset:2048
	ds_read_b128 v[174:177], v144 offset:3072
	s_add_u32 s10, s10, 0x160000
	s_addc_u32 s11, s11, 0
	s_mov_b32 m0, s36
	v_lshl_add_u64 v[226:227], s[10:11], 0, v[142:143]
	ds_read_b128 v[178:181], v190 offset:32768
	ds_read_b128 v[192:195], v190 offset:33792
	ds_read_b128 v[196:199], v190 offset:34816
	ds_read_b128 v[200:203], v190 offset:35840
	ds_read_b128 v[204:207], v190 offset:36864
	ds_read_b128 v[208:211], v190 offset:37888
	ds_read_b128 v[212:215], v190 offset:38912
	ds_read_b128 v[216:219], v190 offset:39936
	global_load_lds_dwordx4 v[226:227], off
	v_lshl_add_u64 v[226:227], s[10:11], 0, v[138:139]
	s_mov_b32 m0, s37
	s_nop 0
	global_load_lds_dwordx4 v[226:227], off
	s_waitcnt vmcnt(8)
	s_waitcnt lgkmcnt(0)
	s_barrier
	s_setprio 1
	s_waitcnt lgkmcnt(0)
	v_mfma_f32_16x16x32_bf16 v[124:127], v[128:131], v[178:181], v[124:127]
	v_mfma_f32_16x16x32_bf16 v[120:123], v[154:157], v[178:181], v[120:123]
	v_mfma_f32_16x16x32_bf16 v[108:111], v[128:131], v[196:199], v[108:111]
	v_mfma_f32_16x16x32_bf16 v[104:107], v[154:157], v[196:199], v[104:107]
	v_mfma_f32_16x16x32_bf16 v[92:95], v[128:131], v[204:207], v[92:95]
	v_mfma_f32_16x16x32_bf16 v[88:91], v[154:157], v[204:207], v[88:91]
	v_mfma_f32_16x16x32_bf16 v[76:79], v[128:131], v[212:215], v[76:79]
	v_mfma_f32_16x16x32_bf16 v[72:75], v[154:157], v[212:215], v[72:75]
	v_mfma_f32_16x16x32_bf16 v[124:127], v[132:135], v[192:195], v[124:127]
	v_mfma_f32_16x16x32_bf16 v[120:123], v[158:161], v[192:195], v[120:123]
	v_mfma_f32_16x16x32_bf16 v[108:111], v[132:135], v[200:203], v[108:111]
	v_mfma_f32_16x16x32_bf16 v[104:107], v[158:161], v[200:203], v[104:107]
	v_mfma_f32_16x16x32_bf16 v[92:95], v[132:135], v[208:211], v[92:95]
	v_mfma_f32_16x16x32_bf16 v[88:91], v[158:161], v[208:211], v[88:91]
	v_mfma_f32_16x16x32_bf16 v[76:79], v[132:135], v[216:219], v[76:79]
	v_mfma_f32_16x16x32_bf16 v[72:75], v[158:161], v[216:219], v[72:75]
	s_setprio 0
	s_setprio 1
	v_mfma_f32_16x16x32_bf16 v[116:119], v[162:165], v[178:181], v[116:119]
	v_mfma_f32_16x16x32_bf16 v[112:115], v[170:173], v[178:181], v[112:115]
	v_mfma_f32_16x16x32_bf16 v[100:103], v[162:165], v[196:199], v[100:103]
	v_mfma_f32_16x16x32_bf16 v[96:99], v[170:173], v[196:199], v[96:99]
	v_mfma_f32_16x16x32_bf16 v[84:87], v[162:165], v[204:207], v[84:87]
	v_mfma_f32_16x16x32_bf16 v[80:83], v[170:173], v[204:207], v[80:83]
	v_mfma_f32_16x16x32_bf16 v[68:71], v[162:165], v[212:215], v[68:71]
	v_mfma_f32_16x16x32_bf16 v[64:67], v[170:173], v[212:215], v[64:67]
	v_mfma_f32_16x16x32_bf16 v[116:119], v[166:169], v[192:195], v[116:119]
	v_mfma_f32_16x16x32_bf16 v[112:115], v[174:177], v[192:195], v[112:115]
	v_mfma_f32_16x16x32_bf16 v[100:103], v[166:169], v[200:203], v[100:103]
	v_mfma_f32_16x16x32_bf16 v[96:99], v[174:177], v[200:203], v[96:99]
	v_mfma_f32_16x16x32_bf16 v[84:87], v[166:169], v[208:211], v[84:87]
	v_mfma_f32_16x16x32_bf16 v[80:83], v[174:177], v[208:211], v[80:83]
	v_mfma_f32_16x16x32_bf16 v[68:71], v[166:169], v[216:219], v[68:71]
	v_mfma_f32_16x16x32_bf16 v[64:67], v[174:177], v[216:219], v[64:67]
	s_setprio 0
	s_barrier
; #define PG8_STAGE(bufoff, gbase, voff) do { _Pragma("unroll") for (int _i = 0; _i < 2; ++_i) \
;         __builtin_amdgcn_global_load_lds((const unsigned*)((const char*)(gbase) + (voff)[_i]), (PG8_LAS unsigned*)(lds + (bufoff) + ldsw + _i * 8192), 16, 0, 0); } while (0)
; #define PG8_LDA(dst, b, h) do { _Pragma("unroll") for (int m = 0; m < 4; ++m) _Pragma("unroll") for (int k = 0; k < 2; ++k) dst[m][k] = *(const PG8_LAS bf16x8*)(lds + PG8_SA(b, h) + aoff + m * 2048 + k * 1024); } while (0)
; #define PG8_MMA(ai, bj, At, Bt) do { __builtin_amdgcn_s_setprio(1); _Pragma("unroll") for (int m = 0; m < 4; ++m) _Pragma("unroll") for (int n = 0; n < 2; ++n) _Pragma("unroll") for (int k = 0; k < 2; ++k) \
;         acc[ai][bj][m][n] = __builtin_amdgcn_mfma_f32_16x16x32_bf16(Bt[n][k], At[m][k], acc[ai][bj][m][n], 0, 0, 0); __builtin_amdgcn_s_setprio(0); } while (0)
; #define PG8_WAIT_V(n) asm volatile("s_waitcnt vmcnt(" #n ")" ::: "memory")
; #define PG8_WAIT_L(n) asm volatile("s_waitcnt lgkmcnt(" #n ")" ::: "memory")
; #define PG8_BAR __builtin_amdgcn_s_barrier()
; #define PG8_SCHED __builtin_amdgcn_sched_barrier(0)
; template <class Epi, class Sched, bool ALIGN_EPI = false, bool SP2 = false>
; __device__ __forceinline__ void gemm_phase(PG8_LAS unsigned char* lds, const Gemm g, const Sched& S, const Epi& E) {
;     ...
;             PG8_LDA(At, 1, 1); PG8_STAGE(PG8_SB(1, 0), b3, voffB); PG8_STAGE(PG8_SB(1, 1), b3 + hstep, voffB); PG8_STAGE(PG8_SA(1, 0), a3, voffA);
;             PG8_WAIT_V(8); PG8_WAIT_L(0); PG8_BAR; PG8_MMA(1, 0, At, B0); PG8_MMA(1, 1, At, B1); PG8_BAR; PG8_SCHED;
;     ...
;         if constexpr (ALIGN_EPI) { if (wr == 0) PG8_BAR; }
	s_add_i32 s10, s52, s23
	v_lshl_add_u64 v[182:183], v[182:183], 0, s[18:19]
	s_mov_b32 m0, s10
	ds_read_b128 v[178:181], v190 offset:49152
	ds_read_b128 v[192:195], v190 offset:50176
	ds_read_b128 v[196:199], v190 offset:51200
	ds_read_b128 v[200:203], v190 offset:52224
	ds_read_b128 v[204:207], v190 offset:53248
	ds_read_b128 v[208:211], v190 offset:54272
	ds_read_b128 v[212:215], v190 offset:55296
	ds_read_b128 v[216:219], v190 offset:56320
	global_load_lds_dwordx4 v[182:183], off
	s_add_i32 m0, s10, 0x2000
	s_add_u32 s2, s2, 0x160080
	v_lshl_add_u64 v[182:183], v[220:221], 0, s[18:19]
	s_addc_u32 s3, s3, 0
	s_add_i32 s10, s53, s23
	global_load_lds_dwordx4 v[182:183], off
	v_lshl_add_u64 v[182:183], s[2:3], 0, v[140:141]
	s_mov_b32 m0, s10
	s_nop 0
	global_load_lds_dwordx4 v[182:183], off
	v_lshl_add_u64 v[182:183], s[2:3], 0, v[136:137]
	s_add_i32 m0, s10, 0x2000
	s_nop 0
	global_load_lds_dwordx4 v[182:183], off
	v_lshl_add_u64 v[182:183], v[222:223], 0, s[18:19]
	s_mov_b32 m0, s41
	s_nop 0
	global_load_lds_dwordx4 v[182:183], off
	v_lshl_add_u64 v[182:183], v[224:225], 0, s[18:19]
	s_mov_b32 m0, s42
	s_nop 0
	global_load_lds_dwordx4 v[182:183], off
	s_waitcnt vmcnt(8)
	s_waitcnt lgkmcnt(0)
	s_barrier
	s_setprio 1
	s_waitcnt lgkmcnt(0)
	v_mfma_f32_16x16x32_bf16 v[60:63], v[128:131], v[178:181], v[60:63]
	v_mfma_f32_16x16x32_bf16 v[56:59], v[154:157], v[178:181], v[56:59]
	v_mfma_f32_16x16x32_bf16 v[44:47], v[128:131], v[196:199], v[44:47]
	v_mfma_f32_16x16x32_bf16 v[40:43], v[154:157], v[196:199], v[40:43]
	v_mfma_f32_16x16x32_bf16 v[28:31], v[128:131], v[204:207], v[28:31]
	v_mfma_f32_16x16x32_bf16 v[24:27], v[154:157], v[204:207], v[24:27]
	v_mfma_f32_16x16x32_bf16 v[12:15], v[128:131], v[212:215], v[12:15]
	v_mfma_f32_16x16x32_bf16 v[8:11], v[154:157], v[212:215], v[8:11]
	v_mfma_f32_16x16x32_bf16 v[60:63], v[132:135], v[192:195], v[60:63]
	v_mfma_f32_16x16x32_bf16 v[56:59], v[158:161], v[192:195], v[56:59]
	v_mfma_f32_16x16x32_bf16 v[44:47], v[132:135], v[200:203], v[44:47]
	v_mfma_f32_16x16x32_bf16 v[40:43], v[158:161], v[200:203], v[40:43]
	v_mfma_f32_16x16x32_bf16 v[28:31], v[132:135], v[208:211], v[28:31]
	v_mfma_f32_16x16x32_bf16 v[24:27], v[158:161], v[208:211], v[24:27]
	v_mfma_f32_16x16x32_bf16 v[12:15], v[132:135], v[216:219], v[12:15]
	v_mfma_f32_16x16x32_bf16 v[8:11], v[158:161], v[216:219], v[8:11]
	s_setprio 0
	s_setprio 1
	v_mfma_f32_16x16x32_bf16 v[52:55], v[162:165], v[178:181], v[52:55]
	v_mfma_f32_16x16x32_bf16 v[48:51], v[170:173], v[178:181], v[48:51]
	v_mfma_f32_16x16x32_bf16 v[36:39], v[162:165], v[196:199], v[36:39]
	v_mfma_f32_16x16x32_bf16 v[32:35], v[170:173], v[196:199], v[32:35]
	v_mfma_f32_16x16x32_bf16 v[20:23], v[162:165], v[204:207], v[20:23]
	v_mfma_f32_16x16x32_bf16 v[16:19], v[170:173], v[204:207], v[16:19]
	v_mfma_f32_16x16x32_bf16 v[4:7], v[162:165], v[212:215], v[4:7]
	v_mfma_f32_16x16x32_bf16 v[0:3], v[170:173], v[212:215], v[0:3]
	v_mfma_f32_16x16x32_bf16 v[52:55], v[166:169], v[192:195], v[52:55]
	v_mfma_f32_16x16x32_bf16 v[48:51], v[174:177], v[192:195], v[48:51]
	v_mfma_f32_16x16x32_bf16 v[36:39], v[166:169], v[200:203], v[36:39]
	v_mfma_f32_16x16x32_bf16 v[32:35], v[174:177], v[200:203], v[32:35]
	v_mfma_f32_16x16x32_bf16 v[20:23], v[166:169], v[208:211], v[20:23]
	v_mfma_f32_16x16x32_bf16 v[16:19], v[174:177], v[208:211], v[16:19]
	v_mfma_f32_16x16x32_bf16 v[4:7], v[166:169], v[216:219], v[4:7]
	v_mfma_f32_16x16x32_bf16 v[0:3], v[174:177], v[216:219], v[0:3]
	s_setprio 0
	s_add_i32 s51, s51, 2
	s_add_u32 s0, s0, 0x100
	s_addc_u32 s1, s1, 0
	s_add_u32 s34, s34, 0x100
	s_addc_u32 s35, s35, 0
	s_cmpk_gt_u32 s51, 0x55
	s_barrier
	s_cbranch_scc0 .LBB0_1124
	s_and_b64 vcc, exec, s[20:21]
	s_cbranch_vccz .LBB0_1127
	s_barrier
